# ret_unit_a: V loads issued with the second q/k load batch (one load round trip less per retention chunk unit)
# speedup vs baseline: 1.0169x; 1.0014x over previous
; #define LAS __attribute__((address_space(3)))
; template <bool WITH_K>
; __device__ __forceinline__ void ret_load_qk(PR P, LAS bf16_t* QP, LAS bf16_t* KB, unsigned (&kth)[4][4], const int tidv, const int row0, const int n, const int h, const float kd0, const float g32) {
;     const bf16_t* PS = (const bf16_t*)(P.ws + WS_BIG); const float* rc = (const float*)(P.ws + WS_ROPE); const float* rs = rc + 2052 * 64;
;     float kd = kd0;
; #pragma unroll
;     for (int it = 0; it < 4; ++it) { const int idx = it * 512 + tidv, i = idx >> 4, f = (idx & 15) * 4;
;         const bf16_t* src = PS + (size_t)(row0 + i) * NCOLS + 1792 + h * 128;
;         const u32x2 q1 = *(const u32x2*)(src + f), q2 = *(const u32x2*)(src + 64 + f);
;         u32x2 k1 = (u32x2){0u, 0u}, k2 = k1; if (WITH_K) { k1 = *(const u32x2*)(src + 512 + f); k2 = *(const u32x2*)(src + 576 + f); }
;         const float4 cs = *(const float4*)(rc + (size_t)(n * 128 + i) * 64 + f), sn = *(const float4*)(rs + (size_t)(n * 128 + i) * 64 + f);
;         const float c4[4] = {cs.x, cs.y, cs.z, cs.w}, s4[4] = {sn.x, sn.y, sn.z, sn.w};
;         const float qa[4] = {lo_bf(q1.x), hi_bf(q1.x), lo_bf(q1.y), hi_bf(q1.y)}, qb[4] = {lo_bf(q2.x), hi_bf(q2.x), lo_bf(q2.y), hi_bf(q2.y)};
;         float qo1[4], qo2[4];
; #pragma unroll
;         for (int x = 0; x < 4; ++x) { qo1[x] = qa[x] * c4[x] - qb[x] * s4[x]; qo2[x] = qa[x] * s4[x] + qb[x] * c4[x]; }
;         u32x2 w; w.x = pg8::cvt_pk_bf16(qo1[0], qo1[1]); w.y = pg8::cvt_pk_bf16(qo1[2], qo1[3]); *(LAS u32x2*)(QP + i * RS + f) = w;
;         w.x = pg8::cvt_pk_bf16(qo2[0], qo2[1]); w.y = pg8::cvt_pk_bf16(qo2[2], qo2[3]); *(LAS u32x2*)(QP + i * RS + 64 + f) = w;
;         if (WITH_K) {
;             const float ka[4] = {lo_bf(k1.x), hi_bf(k1.x), lo_bf(k1.y), hi_bf(k1.y)}, kb[4] = {lo_bf(k2.x), hi_bf(k2.x), lo_bf(k2.y), hi_bf(k2.y)};
;             float ko1[4], ko2[4];
; #pragma unroll
;             for (int x = 0; x < 4; ++x) { ko1[x] = (ka[x] * c4[x] - kb[x] * s4[x]) * 0.08838834764831845f; ko2[x] = (ka[x] * s4[x] + kb[x] * c4[x]) * 0.08838834764831845f; }
;             w.x = pg8::cvt_pk_bf16(ko1[0], ko1[1]); w.y = pg8::cvt_pk_bf16(ko1[2], ko1[3]); *(LAS u32x2*)(KB + i * RS + f) = w;
;             w.x = pg8::cvt_pk_bf16(ko2[0], ko2[1]); w.y = pg8::cvt_pk_bf16(ko2[2], ko2[3]); *(LAS u32x2*)(KB + i * RS + 64 + f) = w;
.LBB0_618:
	s_add_i32 s8, s2, s55
	s_ashr_i32 s30, s8, 4
	s_and_b32 s12, s30, 3
	v_cvt_f32_ubyte0_e32 v0, s12
	v_sub_f32_e32 v0, 0xc0a00000, v0
	v_cmp_gt_f32_e32 vcc, s21, v0
	s_and_b64 s[8:9], vcc, exec
	s_cselect_b32 s8, 0xffffffc0, 0
	v_cndmask_b32_e32 v1, 0, v56, vcc
	v_add_f32_e32 v0, v0, v1
	v_exp_f32_e32 v0, v0
	v_mbcnt_lo_u32_b32 v11, -1, 0
	v_mbcnt_hi_u32_b32 v11, -1, v11
	s_nop 0
	v_add_u32_e32 v10, s33, v11
	v_ldexp_f32 v0, v0, s8
	v_sub_f32_e32 v52, 1.0, v0
	v_cmp_gt_f32_e32 vcc, s22, v52
	s_and_b64 s[8:9], vcc, exec
	s_cselect_b32 s31, 32, 0
	s_lshl_b32 s8, s30, 9
	s_and_b32 s8, s8, 0xfffff800
	v_ashrrev_i32_e32 v61, 4, v10
	s_or_b32 s29, s8, s6
	v_lshlrev_b32_e32 v0, 2, v11
	v_and_b32_e32 v60, 60, v0
	v_add_u32_e32 v0, s29, v61
	v_lshlrev_b32_e32 v28, 2, v60
	v_mad_i64_i32 v[0:1], s[8:9], v0, s23, v[30:31]
	s_lshl_b32 s12, s12, 8
	v_lshl_add_u64 v[6:7], s[14:15], 0, v[28:29]
	v_lshl_add_u64 v[4:5], s[16:17], 0, v[28:29]
	v_lshlrev_b32_e32 v28, 1, v60
	v_lshl_add_u64 v[0:1], v[0:1], 0, s[12:13]
	v_lshl_add_u64 v[2:3], v[0:1], 0, v[28:29]
	v_cndmask_b32_e32 v53, 0, v57, vcc
	v_add_co_u32_e32 v8, vcc, s24, v2
	s_nop 1
	v_addc_co_u32_e32 v9, vcc, 0, v3, vcc
	v_lshl_add_u64 v[2:3], v[2:3], 0, s[18:19]
	global_load_dwordx2 v[8:9], v[8:9], off offset:1536
	s_nop 0
	global_load_dwordx2 v[20:21], v[2:3], off offset:128
	global_load_dwordx2 v[24:25], v[2:3], off offset:1024
	global_load_dwordx2 v[26:27], v[2:3], off offset:1152
	v_add_u32_e32 v2, s6, v61
	v_ashrrev_i32_e32 v3, 31, v2
	v_lshlrev_b64 v[2:3], 8, v[2:3]
	v_lshl_add_u64 v[12:13], v[4:5], 0, v[2:3]
	v_lshl_add_u64 v[2:3], v[6:7], 0, v[2:3]
	global_load_dwordx4 v[12:15], v[12:13], off
	s_nop 0
	global_load_dwordx4 v[16:19], v[2:3], off
	v_add_u32_e32 v2, 0x200, v10
	v_ashrrev_i32_e32 v63, 4, v2
	v_add_u32_e32 v2, s6, v63
	v_ashrrev_i32_e32 v3, 31, v2
	v_lshlrev_b64 v[22:23], 8, v[2:3]
	v_add_u32_e32 v2, s29, v63
	v_mad_i64_i32 v[2:3], s[8:9], v2, s23, v[30:31]
	v_lshl_add_u64 v[2:3], v[2:3], 0, s[12:13]
	v_lshl_add_u64 v[34:35], v[2:3], 0, v[28:29]
	v_add_co_u32_e32 v36, vcc, s24, v34
	v_lshl_add_u64 v[32:33], v[6:7], 0, v[22:23]
	s_nop 0
	v_addc_co_u32_e32 v37, vcc, 0, v35, vcc
	v_lshl_add_u64 v[34:35], v[34:35], 0, s[18:19]
	global_load_dwordx2 v[44:45], v[36:37], off offset:1536
	global_load_dwordx2 v[46:47], v[34:35], off offset:128
	v_lshl_add_u64 v[22:23], v[4:5], 0, v[22:23]
	global_load_dwordx4 v[36:39], v[22:23], off
	global_load_dwordx4 v[40:43], v[32:33], off
	global_load_dwordx2 v[48:49], v[34:35], off offset:1024
	global_load_dwordx2 v[50:51], v[34:35], off offset:1152
	v_ldexp_f32 v22, v52, s31
	v_log_f32_e32 v22, v22
	v_mul_lo_u32 v23, v61, s25
	v_add3_u32 v72, 0, v23, v28
	v_sub_f32_e32 v62, v22, v53
	s_waitcnt vmcnt(0)
	v_lshlrev_b32_e32 v32, 16, v20
	v_lshlrev_b32_e32 v22, 16, v8
	v_and_b32_e32 v23, 0xffff0000, v8
	v_and_b32_e32 v33, 0xffff0000, v20
	v_lshlrev_b32_e32 v8, 16, v9
	v_and_b32_e32 v9, 0xffff0000, v9
	v_lshlrev_b32_e32 v20, 16, v21
	v_and_b32_e32 v21, 0xffff0000, v21
	v_pk_mul_f32 v[54:55], v[12:13], v[32:33]
	v_pk_mul_f32 v[64:65], v[12:13], v[22:23]
	v_pk_mul_f32 v[66:67], v[14:15], v[20:21]
	v_pk_mul_f32 v[68:69], v[14:15], v[8:9]
	v_lshlrev_b32_e32 v34, 16, v24
	v_and_b32_e32 v35, 0xffff0000, v24
	v_lshlrev_b32_e32 v52, 16, v26
	v_and_b32_e32 v53, 0xffff0000, v26
	v_pk_fma_f32 v[22:23], v[16:17], v[22:23], v[54:55] neg_lo:[0,0,1] neg_hi:[0,0,1]
	v_pk_fma_f32 v[32:33], v[16:17], v[32:33], v[64:65]
	v_pk_fma_f32 v[8:9], v[18:19], v[8:9], v[66:67] neg_lo:[0,0,1] neg_hi:[0,0,1]
	v_pk_fma_f32 v[20:21], v[18:19], v[20:21], v[68:69]
	v_pk_mul_f32 v[70:71], v[12:13], v[34:35]
	v_pk_mul_f32 v[12:13], v[12:13], v[52:53]
	v_cvt_pk_bf16_f32 v22, v22, v23
	v_cvt_pk_bf16_f32 v23, v8, v9
	v_cvt_pk_bf16_f32 v8, v32, v33
	v_cvt_pk_bf16_f32 v9, v20, v21
	ds_write2_b64 v72, v[22:23], v[8:9] offset1:16
	v_pk_fma_f32 v[8:9], v[16:17], v[34:35], v[12:13] neg_lo:[0,0,1] neg_hi:[0,0,1]
	v_pk_fma_f32 v[52:53], v[16:17], v[52:53], v[70:71]
	v_pk_mul_f32 v[22:23], v[8:9], s[20:21] op_sel_hi:[1,0]
	v_lshlrev_b32_e32 v8, 16, v25
	v_and_b32_e32 v9, 0xffff0000, v25
	v_lshlrev_b32_e32 v12, 16, v27
	v_and_b32_e32 v13, 0xffff0000, v27
	v_pk_mul_f32 v[16:17], v[14:15], v[8:9]
	v_pk_mul_f32 v[20:21], v[52:53], s[20:21] op_sel_hi:[1,0]
	v_pk_fma_f32 v[16:17], v[18:19], v[12:13], v[16:17]
	v_pk_mul_f32 v[12:13], v[14:15], v[12:13]
	v_pk_mul_f32 v[24:25], v[16:17], s[20:21] op_sel_hi:[1,0]
	v_pk_fma_f32 v[8:9], v[18:19], v[8:9], v[12:13] neg_lo:[0,0,1] neg_hi:[0,0,1]
	v_cvt_pk_bf16_f32 v12, v20, v21
	v_pk_mul_f32 v[26:27], v[8:9], s[20:21] op_sel_hi:[1,0]
	v_cvt_pk_bf16_f32 v8, v22, v23
	v_cvt_pk_bf16_f32 v9, v26, v27
	v_cvt_pk_bf16_f32 v13, v24, v25
	v_add_u32_e32 v14, 0x8800, v72
	ds_write2_b64 v14, v[8:9], v[12:13] offset1:16
	v_lshlrev_b32_e32 v12, 16, v46
	v_and_b32_e32 v13, 0xffff0000, v46
	v_lshlrev_b32_e32 v8, 16, v44
	v_and_b32_e32 v9, 0xffff0000, v44
	v_pk_mul_f32 v[14:15], v[36:37], v[12:13]
	v_lshlrev_b32_e32 v16, 16, v47
	v_pk_fma_f32 v[14:15], v[40:41], v[8:9], v[14:15] neg_lo:[0,0,1] neg_hi:[0,0,1]
	v_pk_mul_f32 v[8:9], v[36:37], v[8:9]
	v_and_b32_e32 v17, 0xffff0000, v47
	v_pk_fma_f32 v[8:9], v[40:41], v[12:13], v[8:9]
	v_lshlrev_b32_e32 v12, 16, v45
	v_and_b32_e32 v13, 0xffff0000, v45
	v_pk_mul_f32 v[18:19], v[38:39], v[16:17]
	v_cvt_pk_bf16_f32 v14, v14, v15
	v_pk_fma_f32 v[18:19], v[42:43], v[12:13], v[18:19] neg_lo:[0,0,1] neg_hi:[0,0,1]
	v_pk_mul_f32 v[12:13], v[38:39], v[12:13]
	v_cvt_pk_bf16_f32 v15, v18, v19
	v_pk_fma_f32 v[12:13], v[42:43], v[16:17], v[12:13]
	v_mul_lo_u32 v16, v63, s25
	v_add3_u32 v16, 0, v16, v28
	v_cvt_pk_bf16_f32 v8, v8, v9
; #define LAS __attribute__((address_space(3)))
; template <bool WITH_K>
; __device__ __forceinline__ void ret_load_qk(PR P, LAS bf16_t* QP, LAS bf16_t* KB, unsigned (&kth)[4][4], const int tidv, const int row0, const int n, const int h, const float kd0, const float g32) {
;     const bf16_t* PS = (const bf16_t*)(P.ws + WS_BIG); const float* rc = (const float*)(P.ws + WS_ROPE); const float* rs = rc + 2052 * 64;
;     float kd = kd0;
; #pragma unroll
;     for (int it = 0; it < 4; ++it) { const int idx = it * 512 + tidv, i = idx >> 4, f = (idx & 15) * 4;
;         const bf16_t* src = PS + (size_t)(row0 + i) * NCOLS + 1792 + h * 128;
;         const u32x2 q1 = *(const u32x2*)(src + f), q2 = *(const u32x2*)(src + 64 + f);
;         u32x2 k1 = (u32x2){0u, 0u}, k2 = k1; if (WITH_K) { k1 = *(const u32x2*)(src + 512 + f); k2 = *(const u32x2*)(src + 576 + f); }
;         const float4 cs = *(const float4*)(rc + (size_t)(n * 128 + i) * 64 + f), sn = *(const float4*)(rs + (size_t)(n * 128 + i) * 64 + f);
;         const float c4[4] = {cs.x, cs.y, cs.z, cs.w}, s4[4] = {sn.x, sn.y, sn.z, sn.w};
;         const float qa[4] = {lo_bf(q1.x), hi_bf(q1.x), lo_bf(q1.y), hi_bf(q1.y)}, qb[4] = {lo_bf(q2.x), hi_bf(q2.x), lo_bf(q2.y), hi_bf(q2.y)};
;         float qo1[4], qo2[4];
; #pragma unroll
;         for (int x = 0; x < 4; ++x) { qo1[x] = qa[x] * c4[x] - qb[x] * s4[x]; qo2[x] = qa[x] * s4[x] + qb[x] * c4[x]; }
;         u32x2 w; w.x = pg8::cvt_pk_bf16(qo1[0], qo1[1]); w.y = pg8::cvt_pk_bf16(qo1[2], qo1[3]); *(LAS u32x2*)(QP + i * RS + f) = w;
;         w.x = pg8::cvt_pk_bf16(qo2[0], qo2[1]); w.y = pg8::cvt_pk_bf16(qo2[2], qo2[3]); *(LAS u32x2*)(QP + i * RS + 64 + f) = w;
;         if (WITH_K) {
;             const float ka[4] = {lo_bf(k1.x), hi_bf(k1.x), lo_bf(k1.y), hi_bf(k1.y)}, kb[4] = {lo_bf(k2.x), hi_bf(k2.x), lo_bf(k2.y), hi_bf(k2.y)};
;             float ko1[4], ko2[4];
; #pragma unroll
;             for (int x = 0; x < 4; ++x) { ko1[x] = (ka[x] * c4[x] - kb[x] * s4[x]) * 0.08838834764831845f; ko2[x] = (ka[x] * s4[x] + kb[x] * c4[x]) * 0.08838834764831845f; }
;             w.x = pg8::cvt_pk_bf16(ko1[0], ko1[1]); w.y = pg8::cvt_pk_bf16(ko1[2], ko1[3]); *(LAS u32x2*)(KB + i * RS + f) = w;
;             w.x = pg8::cvt_pk_bf16(ko2[0], ko2[1]); w.y = pg8::cvt_pk_bf16(ko2[2], ko2[3]); *(LAS u32x2*)(KB + i * RS + 64 + f) = w;
	v_cvt_pk_bf16_f32 v9, v12, v13
	ds_write2_b64 v16, v[14:15], v[8:9] offset1:16
	v_lshlrev_b32_e32 v8, 16, v48
	v_and_b32_e32 v9, 0xffff0000, v48
	v_lshlrev_b32_e32 v12, 16, v50
	v_and_b32_e32 v13, 0xffff0000, v50
	v_pk_mul_f32 v[14:15], v[36:37], v[8:9]
	s_nop 0
	v_pk_fma_f32 v[14:15], v[40:41], v[12:13], v[14:15]
	v_pk_mul_f32 v[12:13], v[36:37], v[12:13]
	v_pk_mul_f32 v[32:33], v[14:15], s[20:21] op_sel_hi:[1,0]
	v_pk_fma_f32 v[8:9], v[40:41], v[8:9], v[12:13] neg_lo:[0,0,1] neg_hi:[0,0,1]
	v_lshlrev_b32_e32 v12, 16, v51
	v_pk_mul_f32 v[34:35], v[8:9], s[20:21] op_sel_hi:[1,0]
	v_lshlrev_b32_e32 v8, 16, v49
	v_and_b32_e32 v9, 0xffff0000, v49
	v_and_b32_e32 v13, 0xffff0000, v51
	v_pk_mul_f32 v[14:15], v[38:39], v[8:9]
	s_nop 0
	v_pk_fma_f32 v[14:15], v[42:43], v[12:13], v[14:15]
	v_pk_mul_f32 v[12:13], v[38:39], v[12:13]
	v_pk_mul_f32 v[36:37], v[14:15], s[20:21] op_sel_hi:[1,0]
	v_pk_fma_f32 v[8:9], v[42:43], v[8:9], v[12:13] neg_lo:[0,0,1] neg_hi:[0,0,1]
	v_cvt_pk_bf16_f32 v12, v32, v33
	v_pk_mul_f32 v[38:39], v[8:9], s[20:21] op_sel_hi:[1,0]
	v_cvt_pk_bf16_f32 v8, v34, v35
	v_cvt_pk_bf16_f32 v9, v38, v39
	v_cvt_pk_bf16_f32 v13, v36, v37
	v_add_u32_e32 v14, 0x8800, v16
	ds_write2_b64 v14, v[8:9], v[12:13] offset1:16
	v_add_u32_e32 v8, 0x400, v10
	v_ashrrev_i32_e32 v90, 4, v8
	v_add_u32_e32 v8, s29, v90
	v_mad_i64_i32 v[8:9], s[8:9], v8, s23, v[30:31]
	v_lshl_add_u64 v[8:9], v[8:9], 0, s[12:13]
	v_lshl_add_u64 v[12:13], v[8:9], 0, v[28:29]
	v_add_co_u32_e32 v14, vcc, s24, v12
	v_add_u32_e32 v48, 0x600, v10
	s_nop 0
	v_addc_co_u32_e32 v15, vcc, 0, v13, vcc
	v_lshl_add_u64 v[12:13], v[12:13], 0, s[18:19]
	global_load_dwordx2 v[40:41], v[14:15], off offset:1536
	global_load_dwordx2 v[42:43], v[12:13], off offset:128
	global_load_dwordx2 v[44:45], v[12:13], off offset:1024
	global_load_dwordx2 v[46:47], v[12:13], off offset:1152
	v_add_u32_e32 v12, s6, v90
	v_ashrrev_i32_e32 v13, 31, v12
	v_ashrrev_i32_e32 v91, 4, v48
	v_lshlrev_b64 v[16:17], 8, v[12:13]
	v_add_u32_e32 v49, s29, v91
	v_lshl_add_u64 v[12:13], v[4:5], 0, v[16:17]
	v_add_u32_e32 v48, s6, v91
	v_mad_i64_i32 v[50:51], s[8:9], v49, s23, v[30:31]
	global_load_dwordx4 v[12:15], v[12:13], off
	v_lshl_add_u64 v[16:17], v[6:7], 0, v[16:17]
	v_ashrrev_i32_e32 v49, 31, v48
	v_lshl_add_u64 v[64:65], v[50:51], 0, s[12:13]
	global_load_dwordx4 v[16:19], v[16:17], off
	v_lshlrev_b64 v[48:49], 8, v[48:49]
	v_lshl_add_u64 v[50:51], v[64:65], 0, v[28:29]
	v_lshl_add_u64 v[52:53], v[6:7], 0, v[48:49]
	v_add_co_u32_e32 v6, vcc, s24, v50
	v_lshl_add_u64 v[4:5], v[4:5], 0, v[48:49]
	s_nop 0
	v_addc_co_u32_e32 v7, vcc, 0, v51, vcc
	v_lshl_add_u64 v[50:51], v[50:51], 0, s[18:19]
	global_load_dwordx2 v[68:69], v[50:51], off offset:128
	global_load_dwordx2 v[66:67], v[6:7], off offset:1536
	s_nop 0
	global_load_dwordx4 v[4:7], v[4:5], off
	s_nop 0
	global_load_dwordx4 v[52:55], v[52:53], off
	s_nop 0
	global_load_dwordx2 v[70:71], v[50:51], off offset:1024
	global_load_dwordx2 v[72:73], v[50:51], off offset:1152
	v_lshlrev_b32_e32 v216, 3, v11
	v_and_b32_e32 v216, 0x78, v216
	v_lshlrev_b32_e32 v216, 1, v216
	v_add_u32_e32 v216, s24, v216
	v_mov_b32_e32 v217, 0
	v_lshl_add_u64 v[218:219], v[0:1], 0, v[216:217]
	v_lshl_add_u64 v[220:221], v[2:3], 0, v[216:217]
	v_lshl_add_u64 v[222:223], v[8:9], 0, v[216:217]
	v_lshl_add_u64 v[224:225], v[64:65], 0, v[216:217]
	global_load_dwordx4 v[200:203], v[218:219], off offset:3584
	global_load_dwordx4 v[204:207], v[220:221], off offset:3584
	global_load_dwordx4 v[208:211], v[222:223], off offset:3584
	global_load_dwordx4 v[212:215], v[224:225], off offset:3584
	v_mul_lo_u32 v48, v90, s25
	v_add3_u32 v92, 0, v48, v28
	s_waitcnt vmcnt(14)
	v_lshlrev_b32_e32 v50, 16, v42
	v_lshlrev_b32_e32 v48, 16, v40
	v_and_b32_e32 v49, 0xffff0000, v40
	v_and_b32_e32 v51, 0xffff0000, v42
	v_lshlrev_b32_e32 v40, 16, v41
	v_and_b32_e32 v41, 0xffff0000, v41
	v_lshlrev_b32_e32 v42, 16, v43
	v_and_b32_e32 v43, 0xffff0000, v43
	s_waitcnt vmcnt(13)
	v_lshlrev_b32_e32 v74, 16, v44
	v_and_b32_e32 v75, 0xffff0000, v44
	s_waitcnt vmcnt(12)
	v_lshlrev_b32_e32 v76, 16, v46
	v_and_b32_e32 v77, 0xffff0000, v46
	v_lshlrev_b32_e32 v44, 16, v45
	v_and_b32_e32 v45, 0xffff0000, v45
	v_lshlrev_b32_e32 v46, 16, v47
	v_and_b32_e32 v47, 0xffff0000, v47
	s_waitcnt vmcnt(11)
	v_pk_mul_f32 v[78:79], v[12:13], v[50:51]
	v_pk_mul_f32 v[80:81], v[12:13], v[48:49]
	v_pk_mul_f32 v[82:83], v[14:15], v[42:43]
	v_pk_mul_f32 v[84:85], v[14:15], v[40:41]
	v_pk_mul_f32 v[86:87], v[12:13], v[74:75]
	v_pk_mul_f32 v[12:13], v[12:13], v[76:77]
	v_pk_mul_f32 v[88:89], v[14:15], v[44:45]
	v_pk_mul_f32 v[14:15], v[14:15], v[46:47]
	s_waitcnt vmcnt(10)
	v_pk_fma_f32 v[48:49], v[16:17], v[48:49], v[78:79] neg_lo:[0,0,1] neg_hi:[0,0,1]
	v_pk_fma_f32 v[50:51], v[16:17], v[50:51], v[80:81]
	v_pk_fma_f32 v[40:41], v[18:19], v[40:41], v[82:83] neg_lo:[0,0,1] neg_hi:[0,0,1]
	v_pk_fma_f32 v[42:43], v[18:19], v[42:43], v[84:85]
	v_pk_fma_f32 v[76:77], v[16:17], v[76:77], v[86:87]
	v_pk_fma_f32 v[12:13], v[16:17], v[74:75], v[12:13] neg_lo:[0,0,1] neg_hi:[0,0,1]
	v_pk_fma_f32 v[16:17], v[18:19], v[46:47], v[88:89]
	v_pk_fma_f32 v[14:15], v[18:19], v[44:45], v[14:15] neg_lo:[0,0,1] neg_hi:[0,0,1]
	v_cvt_pk_bf16_f32 v18, v48, v49
	v_cvt_pk_bf16_f32 v19, v40, v41
	v_cvt_pk_bf16_f32 v49, v42, v43
	v_pk_mul_f32 v[40:41], v[76:77], s[20:21] op_sel_hi:[1,0]
	v_pk_mul_f32 v[44:45], v[12:13], s[20:21] op_sel_hi:[1,0]
	v_pk_mul_f32 v[42:43], v[16:17], s[20:21] op_sel_hi:[1,0]
	v_pk_mul_f32 v[46:47], v[14:15], s[20:21] op_sel_hi:[1,0]
	v_cvt_pk_bf16_f32 v12, v44, v45
	v_cvt_pk_bf16_f32 v13, v46, v47
	v_cvt_pk_bf16_f32 v14, v40, v41
	v_cvt_pk_bf16_f32 v15, v42, v43
	v_add_u32_e32 v16, 0x8800, v92
	ds_write2_b64 v16, v[12:13], v[14:15] offset1:16
	s_waitcnt vmcnt(9)
; template <bool WITH_K>
; __device__ __forceinline__ void ret_load_qk(PR P, LAS bf16_t* QP, LAS bf16_t* KB, unsigned (&kth)[4][4], const int tidv, const int row0, const int n, const int h, const float kd0, const float g32) {
;     ...
;     for (int it = 0; it < 4; ++it) { const int idx = it * 512 + tidv, i = idx >> 4, f = (idx & 15) * 4;
;         const bf16_t* src = PS + (size_t)(row0 + i) * NCOLS + 1792 + h * 128;
;         const u32x2 q1 = *(const u32x2*)(src + f), q2 = *(const u32x2*)(src + 64 + f);
;         u32x2 k1 = (u32x2){0u, 0u}, k2 = k1; if (WITH_K) { k1 = *(const u32x2*)(src + 512 + f); k2 = *(const u32x2*)(src + 576 + f); }
;         const float4 cs = *(const float4*)(rc + (size_t)(n * 128 + i) * 64 + f), sn = *(const float4*)(rs + (size_t)(n * 128 + i) * 64 + f);
;         const float c4[4] = {cs.x, cs.y, cs.z, cs.w}, s4[4] = {sn.x, sn.y, sn.z, sn.w};
;         const float qa[4] = {lo_bf(q1.x), hi_bf(q1.x), lo_bf(q1.y), hi_bf(q1.y)}, qb[4] = {lo_bf(q2.x), hi_bf(q2.x), lo_bf(q2.y), hi_bf(q2.y)};
;         float qo1[4], qo2[4];
; #pragma unroll
;         for (int x = 0; x < 4; ++x) { qo1[x] = qa[x] * c4[x] - qb[x] * s4[x]; qo2[x] = qa[x] * s4[x] + qb[x] * c4[x]; }
;         u32x2 w; w.x = pg8::cvt_pk_bf16(qo1[0], qo1[1]); w.y = pg8::cvt_pk_bf16(qo1[2], qo1[3]); *(LAS u32x2*)(QP + i * RS + f) = w;
;         w.x = pg8::cvt_pk_bf16(qo2[0], qo2[1]); w.y = pg8::cvt_pk_bf16(qo2[2], qo2[3]); *(LAS u32x2*)(QP + i * RS + 64 + f) = w;
;         if (WITH_K) {
;             const float ka[4] = {lo_bf(k1.x), hi_bf(k1.x), lo_bf(k1.y), hi_bf(k1.y)}, kb[4] = {lo_bf(k2.x), hi_bf(k2.x), lo_bf(k2.y), hi_bf(k2.y)};
;             float ko1[4], ko2[4];
; #pragma unroll
;             for (int x = 0; x < 4; ++x) { ko1[x] = (ka[x] * c4[x] - kb[x] * s4[x]) * 0.08838834764831845f; ko2[x] = (ka[x] * s4[x] + kb[x] * c4[x]) * 0.08838834764831845f; }
;             w.x = pg8::cvt_pk_bf16(ko1[0], ko1[1]); w.y = pg8::cvt_pk_bf16(ko1[2], ko1[3]); *(LAS u32x2*)(KB + i * RS + f) = w;
;             w.x = pg8::cvt_pk_bf16(ko2[0], ko2[1]); w.y = pg8::cvt_pk_bf16(ko2[2], ko2[3]); *(LAS u32x2*)(KB + i * RS + 64 + f) = w;
;             kth[it][0] = pg8::cvt_pk_bf16(ko1[0] * kd, ko1[1] * kd); kth[it][1] = pg8::cvt_pk_bf16(ko1[2] * kd, ko1[3] * kd);
;             kth[it][2] = pg8::cvt_pk_bf16(ko2[0] * kd, ko2[1] * kd); kth[it][3] = pg8::cvt_pk_bf16(ko2[2] * kd, ko2[3] * kd); kd *= g32; }
	v_lshlrev_b32_e32 v14, 16, v68
	v_and_b32_e32 v15, 0xffff0000, v68
	v_cvt_pk_bf16_f32 v48, v50, v51
	s_waitcnt vmcnt(8)
	v_lshlrev_b32_e32 v12, 16, v66
	v_and_b32_e32 v13, 0xffff0000, v66
	s_waitcnt vmcnt(7)
	v_pk_mul_f32 v[16:17], v[4:5], v[14:15]
	ds_write2_b64 v92, v[18:19], v[48:49] offset1:16
	s_waitcnt vmcnt(6)
	v_pk_fma_f32 v[16:17], v[52:53], v[12:13], v[16:17] neg_lo:[0,0,1] neg_hi:[0,0,1]
	v_pk_mul_f32 v[12:13], v[4:5], v[12:13]
	v_lshlrev_b32_e32 v18, 16, v69
	v_and_b32_e32 v19, 0xffff0000, v69
	v_pk_fma_f32 v[12:13], v[52:53], v[14:15], v[12:13]
	v_lshlrev_b32_e32 v14, 16, v67
	v_and_b32_e32 v15, 0xffff0000, v67
	v_pk_mul_f32 v[48:49], v[6:7], v[18:19]
	v_cvt_pk_bf16_f32 v16, v16, v17
	v_pk_fma_f32 v[48:49], v[54:55], v[14:15], v[48:49] neg_lo:[0,0,1] neg_hi:[0,0,1]
	v_pk_mul_f32 v[14:15], v[6:7], v[14:15]
	v_cvt_pk_bf16_f32 v17, v48, v49
	v_pk_fma_f32 v[14:15], v[54:55], v[18:19], v[14:15]
	v_mul_lo_u32 v18, v91, s25
	v_add3_u32 v18, 0, v18, v28
	v_cvt_pk_bf16_f32 v12, v12, v13
	v_cvt_pk_bf16_f32 v13, v14, v15
	ds_write2_b64 v18, v[16:17], v[12:13] offset1:16
	s_waitcnt vmcnt(5)
	v_lshlrev_b32_e32 v12, 16, v70
	v_and_b32_e32 v13, 0xffff0000, v70
	s_waitcnt vmcnt(4)
	v_lshlrev_b32_e32 v14, 16, v72
	v_and_b32_e32 v15, 0xffff0000, v72
	v_pk_mul_f32 v[16:17], v[4:5], v[12:13]
	v_pk_mul_f32 v[4:5], v[4:5], v[14:15]
	v_pk_fma_f32 v[16:17], v[52:53], v[14:15], v[16:17]
	v_pk_fma_f32 v[4:5], v[52:53], v[12:13], v[4:5] neg_lo:[0,0,1] neg_hi:[0,0,1]
	v_lshlrev_b32_e32 v12, 16, v73
	v_pk_mul_f32 v[50:51], v[4:5], s[20:21] op_sel_hi:[1,0]
	v_lshlrev_b32_e32 v4, 16, v71
	v_and_b32_e32 v5, 0xffff0000, v71
	v_and_b32_e32 v13, 0xffff0000, v73
	v_pk_mul_f32 v[14:15], v[6:7], v[4:5]
	v_pk_mul_f32 v[6:7], v[6:7], v[12:13]
	v_pk_fma_f32 v[14:15], v[54:55], v[12:13], v[14:15]
	v_pk_fma_f32 v[4:5], v[54:55], v[4:5], v[6:7] neg_lo:[0,0,1] neg_hi:[0,0,1]
	v_pk_mul_f32 v[48:49], v[16:17], s[20:21] op_sel_hi:[1,0]
	v_pk_mul_f32 v[52:53], v[14:15], s[20:21] op_sel_hi:[1,0]
	v_pk_mul_f32 v[54:55], v[4:5], s[20:21] op_sel_hi:[1,0]
	v_cvt_pk_bf16_f32 v4, v50, v51
	v_cvt_pk_bf16_f32 v5, v54, v55
	v_cvt_pk_bf16_f32 v6, v48, v49
	v_cvt_pk_bf16_f32 v7, v52, v53
	v_add_u32_e32 v12, 0x8800, v18
	ds_write2_b64 v12, v[4:5], v[6:7] offset1:16
	v_lshlrev_b32_e32 v4, 3, v11
	v_and_b32_e32 v66, 0x78, v4
	v_lshlrev_b32_e32 v28, 1, v66
	v_lshlrev_b32_e32 v79, 1, v61
	v_lshlrev_b32_e32 v78, 1, v63
	v_bfe_u32 v28, v11, 4, 2
	v_ashrrev_i32_e32 v9, 2, v10
	v_and_b32_e32 v8, 15, v11
	v_and_b32_e32 v69, 0xffffffe0, v9
	v_lshlrev_b32_e32 v75, 4, v28
	v_or_b32_e32 v11, v69, v8
	v_mad_u32_u24 v9, v66, s25, v58
	v_add_u32_e32 v73, 0, v75
	v_mul_lo_u32 v77, v11, s25
	v_lshlrev_b32_e32 v76, 1, v90
	v_lshlrev_b32_e32 v74, 1, v91
	v_add_u32_e32 v63, v9, v79
	v_add_u32_e32 v68, v73, v77
	v_add_u32_e32 v64, v9, v78
	v_add_u32_e32 v65, v9, v76
	v_add_u32_e32 v9, v9, v74
	s_waitcnt vmcnt(3)
	ds_write_b16 v63, v200
	ds_write_b16_d16_hi v63, v200 offset:272
	ds_write_b16 v63, v201 offset:544
	ds_write_b16_d16_hi v63, v201 offset:816
	ds_write_b16 v63, v202 offset:1088
	ds_write_b16_d16_hi v63, v202 offset:1360
	ds_write_b16 v63, v203 offset:1632
	ds_write_b16_d16_hi v63, v203 offset:1904
	s_waitcnt vmcnt(2)
	ds_write_b16 v64, v204
	ds_write_b16_d16_hi v64, v204 offset:272
	ds_write_b16 v64, v205 offset:544
	ds_write_b16_d16_hi v64, v205 offset:816
	ds_write_b16 v64, v206 offset:1088
	ds_write_b16_d16_hi v64, v206 offset:1360
	ds_write_b16 v64, v207 offset:1632
	ds_write_b16_d16_hi v64, v207 offset:1904
	s_waitcnt vmcnt(1)
	ds_write_b16 v65, v208
	ds_write_b16_d16_hi v65, v208 offset:272
	ds_write_b16 v65, v209 offset:544
	ds_write_b16_d16_hi v65, v209 offset:816
	ds_write_b16 v65, v210 offset:1088
	ds_write_b16_d16_hi v65, v210 offset:1360
	ds_write_b16 v65, v211 offset:1632
	ds_write_b16_d16_hi v65, v211 offset:1904
	s_waitcnt vmcnt(0)
	ds_write_b16 v9, v212
	ds_write_b16_d16_hi v9, v212 offset:272
	ds_write_b16 v9, v213 offset:544
	ds_write_b16_d16_hi v9, v213 offset:816
	ds_write_b16 v9, v214 offset:1088
	ds_write_b16_d16_hi v9, v214 offset:1360
	ds_write_b16 v9, v215 offset:1632
	ds_write_b16_d16_hi v9, v215 offset:1904
	s_waitcnt lgkmcnt(0)
	s_barrier
	ds_read_b128 v[0:3], v68
	v_and_or_b32 v63, v10, 64, v8
	v_mad_u32_u24 v70, v63, s25, v73
	ds_read_b128 v[4:7], v68 offset:4352
	ds_read_b128 v[8:11], v70 offset:34816
	ds_read_b128 v[12:15], v70 offset:39168
	ds_read_b128 v[80:83], v70 offset:43520
	ds_read_b128 v[84:87], v70 offset:47872
	s_waitcnt lgkmcnt(3)
	v_mfma_f32_16x16x32_bf16 v[16:19], v[0:3], v[8:11], 0
	v_or_b32_e32 v116, 16, v63
	v_or_b32_e32 v117, 32, v63
	v_or_b32_e32 v118, 48, v63
	v_mfma_f32_16x16x32_bf16 v[8:11], v[4:7], v[8:11], 0
	s_waitcnt lgkmcnt(2)
	v_mfma_f32_16x16x32_bf16 v[64:67], v[0:3], v[12:15], 0
	v_mfma_f32_16x16x32_bf16 v[12:15], v[4:7], v[12:15], 0
	s_waitcnt lgkmcnt(1)
	v_mfma_f32_16x16x32_bf16 v[88:91], v[0:3], v[80:83], 0
	v_mfma_f32_16x16x32_bf16 v[80:83], v[4:7], v[80:83], 0
	s_waitcnt lgkmcnt(0)
	v_mfma_f32_16x16x32_bf16 v[0:3], v[0:3], v[84:87], 0
	v_mfma_f32_16x16x32_bf16 v[4:7], v[4:7], v[84:87], 0
	ds_read_b128 v[84:87], v68 offset:64
	ds_read_b128 v[92:95], v68 offset:4416
	ds_read_b128 v[96:99], v70 offset:34880
	ds_read_b128 v[100:103], v70 offset:39232
	s_waitcnt lgkmcnt(1)
	v_mfma_f32_16x16x32_bf16 v[16:19], v[84:87], v[96:99], v[16:19]
	v_mfma_f32_16x16x32_bf16 v[8:11], v[92:95], v[96:99], v[8:11]
	s_waitcnt lgkmcnt(0)
	v_mfma_f32_16x16x32_bf16 v[64:67], v[84:87], v[100:103], v[64:67]
	v_mfma_f32_16x16x32_bf16 v[12:15], v[92:95], v[100:103], v[12:15]
	ds_read_b128 v[96:99], v70 offset:43584
	ds_read_b128 v[100:103], v70 offset:47936
	s_waitcnt lgkmcnt(1)
; #define LAS __attribute__((address_space(3)))
; __device__ __forceinline__ bf16_t f2bf(float f) { unsigned u = __float_as_uint(f); u += 0x7FFFu + ((u >> 16) & 1u); return (bf16_t)(u >> 16); }
; __device__ __forceinline__ void ret_unit_a(PR P, LAS unsigned char* lds, const int bh, const int n, const int wv) {
;     ...
;     for (int ks = 0; ks < 4; ++ks) { bf16x8 aq[2];
; #pragma unroll
;         for (int mt = 0; mt < 2; ++mt) aq[mt] = *(const LAS bf16x8*)(QP + (wr * 32 + mt * 16 + fr) * RS + ks * 32 + fq * 8);
; #pragma unroll
;         for (int nt = 0; nt < 4; ++nt) { const bf16x8 bk = *(const LAS bf16x8*)(KB + (wc * 64 + nt * 16 + fr) * RS + ks * 32 + fq * 8);
; #pragma unroll
;             for (int mt = 0; mt < 2; ++mt) accP[mt][nt] = __builtin_amdgcn_mfma_f32_16x16x32_bf16(aq[mt], bk, accP[mt][nt], 0, 0, 0); }
;         __builtin_amdgcn_sched_barrier(0); }
;     __syncthreads();
;     { float ri[2][4], cj[4];
; #pragma unroll
;       for (int mt = 0; mt < 2; ++mt)
; #pragma unroll
;           for (int j = 0; j < 4; ++j) ri[mt][j] = exp2f(lg2 * (float)(wr * 32 + mt * 16 + fq * 4 + j));
; #pragma unroll
;       for (int nt = 0; nt < 4; ++nt) cj[nt] = exp2f(-lg2 * (float)(wc * 64 + nt * 16 + fr));
; #pragma unroll
;       for (int mt = 0; mt < 2; ++mt)
; #pragma unroll
;           for (int nt = 0; nt < 4; ++nt)
; #pragma unroll
;               for (int j = 0; j < 4; ++j) { const int i = wr * 32 + mt * 16 + fq * 4 + j, jj = wc * 64 + nt * 16 + fr;
;                   const float val = i >= jj ? accP[mt][nt][j] * ri[mt][j] * cj[nt] : 0.f; QP[i * RS + jj] = f2bf(val); } }
	v_mfma_f32_16x16x32_bf16 v[88:91], v[84:87], v[96:99], v[88:91]
	v_mfma_f32_16x16x32_bf16 v[80:83], v[92:95], v[96:99], v[80:83]
	s_waitcnt lgkmcnt(0)
	v_mfma_f32_16x16x32_bf16 v[0:3], v[84:87], v[100:103], v[0:3]
	v_mfma_f32_16x16x32_bf16 v[4:7], v[92:95], v[100:103], v[4:7]
	ds_read_b128 v[84:87], v68 offset:128
	ds_read_b128 v[92:95], v68 offset:4480
	ds_read_b128 v[96:99], v70 offset:34944
	ds_read_b128 v[100:103], v70 offset:39296
	s_waitcnt lgkmcnt(1)
	v_mfma_f32_16x16x32_bf16 v[16:19], v[84:87], v[96:99], v[16:19]
	v_mfma_f32_16x16x32_bf16 v[8:11], v[92:95], v[96:99], v[8:11]
	s_waitcnt lgkmcnt(0)
	v_mfma_f32_16x16x32_bf16 v[64:67], v[84:87], v[100:103], v[64:67]
	v_mfma_f32_16x16x32_bf16 v[96:99], v[92:95], v[100:103], v[12:15]
	s_nop 2
	ds_read_b128 v[12:15], v70 offset:43648
	ds_read_b128 v[100:103], v70 offset:48000
	s_waitcnt lgkmcnt(1)
	v_mfma_f32_16x16x32_bf16 v[88:91], v[84:87], v[12:15], v[88:91]
	v_mfma_f32_16x16x32_bf16 v[80:83], v[92:95], v[12:15], v[80:83]
	s_waitcnt lgkmcnt(0)
	v_mfma_f32_16x16x32_bf16 v[0:3], v[84:87], v[100:103], v[0:3]
	v_mfma_f32_16x16x32_bf16 v[84:87], v[92:95], v[100:103], v[4:7]
	ds_read_b128 v[92:95], v68 offset:192
	ds_read_b128 v[100:103], v68 offset:4544
	s_nop 0
	ds_read_b128 v[4:7], v70 offset:35008
	ds_read_b128 v[104:107], v70 offset:39360
	s_waitcnt lgkmcnt(1)
	v_mfma_f32_16x16x32_bf16 v[108:111], v[92:95], v[4:7], v[16:19]
	v_mfma_f32_16x16x32_bf16 v[12:15], v[100:103], v[4:7], v[8:11]
	s_waitcnt lgkmcnt(0)
	v_mfma_f32_16x16x32_bf16 v[112:115], v[92:95], v[104:107], v[64:67]
	ds_read_b128 v[4:7], v70 offset:43712
	s_nop 1
	ds_read_b128 v[64:67], v70 offset:48064
	v_mfma_f32_16x16x32_bf16 v[8:11], v[100:103], v[104:107], v[96:99]
	s_waitcnt lgkmcnt(1)
	v_mfma_f32_16x16x32_bf16 v[88:91], v[92:95], v[4:7], v[88:91]
	v_mfma_f32_16x16x32_bf16 v[4:7], v[100:103], v[4:7], v[80:83]
	s_waitcnt lgkmcnt(0)
	v_mfma_f32_16x16x32_bf16 v[16:19], v[92:95], v[64:67], v[0:3]
	v_mfma_f32_16x16x32_bf16 v[0:3], v[100:103], v[64:67], v[84:87]
	v_lshl_or_b32 v72, v28, 2, v69
	v_cvt_f32_i32_e32 v28, v72
	v_or_b32_e32 v71, 1, v72
	v_cvt_f32_i32_e32 v65, v71
	v_or_b32_e32 v70, 2, v72
	v_mul_f32_e32 v64, v62, v28
	v_cmp_gt_f32_e32 vcc, s21, v64
	v_mul_f32_e32 v66, v62, v65
	v_or_b32_e32 v69, 3, v72
	v_cndmask_b32_e32 v64, 0, v56, vcc
	v_fmac_f32_e32 v64, v62, v28
	v_exp_f32_e32 v28, v64
	v_cndmask_b32_e32 v64, 0, v59, vcc
	v_cmp_gt_f32_e32 vcc, s21, v66
	v_or_b32_e32 v67, 16, v72
	v_ldexp_f32 v81, v28, v64
	v_cndmask_b32_e32 v66, 0, v56, vcc
	v_fmac_f32_e32 v66, v62, v65
	v_exp_f32_e32 v65, v66
	v_cvt_f32_i32_e32 v66, v70
	v_cndmask_b32_e32 v28, 0, v59, vcc
	v_cvt_f32_i32_e32 v64, v69
	v_ldexp_f32 v84, v65, v28
	v_mul_f32_e32 v28, v62, v66
	v_cmp_gt_f32_e32 vcc, s21, v28
	v_cvt_f32_i32_e32 v80, v67
	s_nop 0
	v_cndmask_b32_e32 v28, 0, v56, vcc
	v_fmac_f32_e32 v28, v62, v66
	v_mul_f32_e32 v66, v62, v64
	v_cndmask_b32_e32 v65, 0, v59, vcc
	v_cmp_gt_f32_e32 vcc, s21, v66
	v_exp_f32_e32 v28, v28
	s_barrier
	v_cndmask_b32_e32 v66, 0, v56, vcc
	v_fmac_f32_e32 v66, v62, v64
	v_exp_f32_e32 v64, v66
	v_ldexp_f32 v85, v28, v65
	v_cndmask_b32_e32 v28, 0, v59, vcc
	v_or_b32_e32 v66, 17, v72
	v_ldexp_f32 v86, v64, v28
	v_cvt_f32_i32_e32 v64, v66
	v_mul_f32_e32 v28, v62, v80
	v_cmp_gt_f32_e32 vcc, s21, v28
	v_mul_f32_e32 v65, v62, v64
	s_nop 0
	v_cndmask_b32_e32 v28, 0, v56, vcc
	v_fmac_f32_e32 v28, v62, v80
	v_cndmask_b32_e32 v80, 0, v59, vcc
	v_cmp_gt_f32_e32 vcc, s21, v65
	v_exp_f32_e32 v28, v28
	v_mul_f32_e32 v16, v81, v16
	v_cndmask_b32_e32 v65, 0, v56, vcc
	v_fmac_f32_e32 v65, v62, v64
	v_exp_f32_e32 v64, v65
	v_or_b32_e32 v65, 18, v72
	v_cvt_f32_i32_e32 v82, v65
	v_ldexp_f32 v87, v28, v80
	v_cndmask_b32_e32 v28, 0, v59, vcc
	v_ldexp_f32 v92, v64, v28
	v_or_b32_e32 v64, 19, v72
	v_cvt_f32_i32_e32 v80, v64
	v_mul_f32_e32 v28, v62, v82
	v_cmp_gt_f32_e32 vcc, s21, v28
	v_mul_f32_e32 v12, v87, v12
	v_mul_f32_e32 v8, v87, v8
	v_cndmask_b32_e32 v28, 0, v56, vcc
	v_fmac_f32_e32 v28, v62, v82
	v_mul_f32_e32 v82, v62, v80
	v_cmp_gt_f32_e64 s[8:9], s21, v82
	v_exp_f32_e32 v28, v28
	v_mul_f32_e32 v4, v87, v4
	v_cndmask_b32_e64 v82, 0, v56, s[8:9]
	v_fmac_f32_e32 v82, v62, v80
	v_exp_f32_e32 v80, v82
	v_cndmask_b32_e32 v82, 0, v59, vcc
	v_ldexp_f32 v93, v28, v82
	v_cndmask_b32_e64 v28, 0, v59, s[8:9]
	v_ldexp_f32 v94, v80, v28
	v_cvt_f32_ubyte0_e32 v28, v63
	v_mul_f32_e64 v80, -v62, v28
	v_cmp_gt_f32_e32 vcc, s21, v80
	v_mul_f32_e32 v0, v87, v0
	s_nop 0
	v_cndmask_b32_e32 v80, 0, v56, vcc
	v_fma_f32 v28, -v62, v28, v80
	v_cvt_f32_ubyte0_e32 v80, v116
	v_mul_f32_e64 v82, -v62, v80
	v_cmp_gt_f32_e64 s[8:9], s21, v82
	v_exp_f32_e32 v28, v28
	s_nop 0
	v_cndmask_b32_e64 v82, 0, v56, s[8:9]
	v_fma_f32 v80, -v62, v80, v82
	v_exp_f32_e32 v80, v80
	v_cndmask_b32_e32 v82, 0, v59, vcc
	v_ldexp_f32 v95, v28, v82
	v_cndmask_b32_e64 v28, 0, v59, s[8:9]
	v_ldexp_f32 v96, v80, v28
	v_cvt_f32_ubyte0_e32 v28, v117
	v_mul_f32_e64 v80, -v62, v28
	v_cmp_gt_f32_e32 vcc, s21, v80
	v_mul_f32_e32 v12, v95, v12
	v_mul_f32_e32 v8, v96, v8
	v_cndmask_b32_e32 v80, 0, v56, vcc
	v_fma_f32 v28, -v62, v28, v80
	v_cvt_f32_ubyte0_e32 v80, v118
	v_mul_f32_e64 v82, -v62, v80
	v_cmp_gt_f32_e64 s[8:9], s21, v82
	v_exp_f32_e32 v28, v28
	s_nop 0
	v_cndmask_b32_e64 v82, 0, v56, s[8:9]
	v_fma_f32 v80, -v62, v80, v82
	v_exp_f32_e32 v80, v80
	v_cndmask_b32_e32 v82, 0, v59, vcc
	v_ldexp_f32 v97, v28, v82
	v_mul_f32_e32 v82, v81, v108
	v_cndmask_b32_e64 v28, 0, v59, s[8:9]
	v_mul_f32_e32 v82, v95, v82
	v_cmp_lt_i32_e32 vcc, v72, v63
	v_ldexp_f32 v98, v80, v28
	v_lshlrev_b32_e32 v28, 1, v63
	v_cndmask_b32_e64 v82, v82, 0, vcc
	v_add_u32_e32 v80, 0, v28
	v_bfe_u32 v83, v82, 16, 1
; __device__ __forceinline__ bf16_t f2bf(float f) { unsigned u = __float_as_uint(f); u += 0x7FFFu + ((u >> 16) & 1u); return (bf16_t)(u >> 16); }
; __device__ __forceinline__ bf16_t* kvb_ptr(unsigned char* ws, int bh) { return (bf16_t*)(bh < 29 ? ws + WS_LA + (size_t)bh * 524288 : ws + WS_WIN + 17301504 + (size_t)(bh - 29) * 524288); }
; __device__ __forceinline__ void ret_unit_a(PR P, LAS unsigned char* lds, const int bh, const int n, const int wv) {
;     ...
;       for (int mt = 0; mt < 2; ++mt)
; #pragma unroll
;           for (int nt = 0; nt < 4; ++nt)
; #pragma unroll
;               for (int j = 0; j < 4; ++j) { const int i = wr * 32 + mt * 16 + fq * 4 + j, jj = wc * 64 + nt * 16 + fr;
;                   const float val = i >= jj ? accP[mt][nt][j] * ri[mt][j] * cj[nt] : 0.f; QP[i * RS + jj] = f2bf(val); } }
	v_add3_u32 v99, v82, v83, s27
	v_mad_u64_u32 v[82:83], s[8:9], v72, s25, v[80:81]
	v_mul_f32_e32 v83, v84, v109
	v_mul_f32_e32 v83, v95, v83
	v_cmp_ge_i32_e64 s[8:9], v71, v63
	ds_write_b16_d16_hi v82, v99
	v_mul_f32_e32 v16, v98, v16
	v_cndmask_b32_e64 v83, 0, v83, s[8:9]
	v_bfe_u32 v99, v83, 16, 1
	v_add3_u32 v83, v83, v99, s27
	ds_write_b16_d16_hi v82, v83 offset:272
	v_mul_f32_e32 v83, v85, v110
	v_mul_f32_e32 v83, v95, v83
	v_cmp_ge_i32_e64 s[8:9], v70, v63
	v_cndmask_b32_e64 v8, v8, 0, vcc
	v_cmp_ge_i32_e32 vcc, v66, v116
	v_cndmask_b32_e64 v83, 0, v83, s[8:9]
	v_bfe_u32 v99, v83, 16, 1
	v_add3_u32 v83, v83, v99, s27
	ds_write_b16_d16_hi v82, v83 offset:544
	v_mul_f32_e32 v83, v86, v111
	v_mul_f32_e32 v83, v95, v83
	v_cmp_ge_i32_e64 s[8:9], v69, v63
	v_mul_f32_e32 v4, v97, v4
	v_mul_f32_e32 v0, v98, v0
	v_cndmask_b32_e64 v83, 0, v83, s[8:9]
	v_bfe_u32 v99, v83, 16, 1
	v_add3_u32 v83, v83, v99, s27
	ds_write_b16_d16_hi v82, v83 offset:816
	v_mul_f32_e32 v83, v81, v112
	v_mul_f32_e32 v83, v96, v83
	v_cmp_ge_i32_e64 s[8:9], v72, v116
	s_nop 1
	v_cndmask_b32_e64 v83, 0, v83, s[8:9]
	v_bfe_u32 v99, v83, 16, 1
	v_add3_u32 v83, v83, v99, s27
	ds_write_b16_d16_hi v82, v83 offset:32
	v_mul_f32_e32 v83, v84, v113
	v_mul_f32_e32 v83, v96, v83
	v_cmp_ge_i32_e64 s[8:9], v71, v116
	s_nop 1
	v_cndmask_b32_e64 v83, 0, v83, s[8:9]
	v_bfe_u32 v99, v83, 16, 1
	v_add3_u32 v83, v83, v99, s27
	ds_write_b16_d16_hi v82, v83 offset:304
	v_mul_f32_e32 v83, v85, v114
	v_mul_f32_e32 v83, v96, v83
	v_cmp_ge_i32_e64 s[8:9], v70, v116
	s_nop 1
	v_cndmask_b32_e64 v83, 0, v83, s[8:9]
	v_bfe_u32 v99, v83, 16, 1
	v_add3_u32 v83, v83, v99, s27
	ds_write_b16_d16_hi v82, v83 offset:576
	v_mul_f32_e32 v83, v86, v115
	v_mul_f32_e32 v83, v96, v83
	v_cmp_ge_i32_e64 s[8:9], v69, v116
	s_nop 1
	v_cndmask_b32_e64 v83, 0, v83, s[8:9]
	v_bfe_u32 v99, v83, 16, 1
	v_add3_u32 v83, v83, v99, s27
	ds_write_b16_d16_hi v82, v83 offset:848
	v_mul_f32_e32 v83, v81, v88
	v_mul_f32_e32 v83, v97, v83
	v_cmp_ge_i32_e64 s[8:9], v72, v117
	s_nop 1
	v_cndmask_b32_e64 v83, 0, v83, s[8:9]
	v_bfe_u32 v88, v83, 16, 1
	v_add3_u32 v83, v83, v88, s27
	ds_write_b16_d16_hi v82, v83 offset:64
	v_mul_f32_e32 v83, v84, v89
	v_mul_f32_e32 v83, v97, v83
	v_cmp_ge_i32_e64 s[8:9], v71, v117
	s_nop 1
	v_cndmask_b32_e64 v83, 0, v83, s[8:9]
	v_bfe_u32 v88, v83, 16, 1
	v_add3_u32 v83, v83, v88, s27
	ds_write_b16_d16_hi v82, v83 offset:336
	v_mul_f32_e32 v83, v85, v90
	v_mul_f32_e32 v83, v97, v83
	v_cmp_ge_i32_e64 s[8:9], v70, v117
	s_nop 1
	v_cndmask_b32_e64 v83, 0, v83, s[8:9]
	v_bfe_u32 v88, v83, 16, 1
	v_add3_u32 v83, v83, v88, s27
	ds_write_b16_d16_hi v82, v83 offset:608
	v_mul_f32_e32 v83, v86, v91
	v_mul_f32_e32 v83, v97, v83
	v_cmp_ge_i32_e64 s[8:9], v69, v117
	s_nop 1
	v_cndmask_b32_e64 v83, 0, v83, s[8:9]
	v_cmp_ge_i32_e64 s[8:9], v72, v118
	v_bfe_u32 v88, v83, 16, 1
	v_add3_u32 v83, v83, v88, s27
	v_cndmask_b32_e64 v16, 0, v16, s[8:9]
	v_bfe_u32 v81, v16, 16, 1
	v_add3_u32 v16, v16, v81, s27
	ds_write_b16_d16_hi v82, v16 offset:96
	v_mul_f32_e32 v16, v84, v17
	v_mul_f32_e32 v16, v98, v16
	v_cmp_ge_i32_e64 s[8:9], v71, v118
	ds_write_b16_d16_hi v82, v83 offset:880
	s_nop 0
	v_cndmask_b32_e64 v16, 0, v16, s[8:9]
	v_bfe_u32 v17, v16, 16, 1
	v_add3_u32 v16, v16, v17, s27
	ds_write_b16_d16_hi v82, v16 offset:368
	v_mul_f32_e32 v16, v85, v18
	v_mul_f32_e32 v16, v98, v16
	v_cmp_ge_i32_e64 s[8:9], v70, v118
	s_nop 1
	v_cndmask_b32_e64 v16, 0, v16, s[8:9]
	v_bfe_u32 v17, v16, 16, 1
	v_add3_u32 v16, v16, v17, s27
	ds_write_b16_d16_hi v82, v16 offset:640
	v_mul_f32_e32 v16, v86, v19
	v_mul_f32_e32 v16, v98, v16
	v_cmp_ge_i32_e64 s[8:9], v69, v118
	s_nop 1
	v_cndmask_b32_e64 v16, 0, v16, s[8:9]
	v_bfe_u32 v17, v16, 16, 1
	v_cmp_ge_i32_e64 s[8:9], v67, v63
	v_add3_u32 v16, v16, v17, s27
	ds_write_b16_d16_hi v82, v16 offset:912
	v_cndmask_b32_e64 v12, 0, v12, s[8:9]
	v_bfe_u32 v16, v12, 16, 1
	v_add3_u32 v12, v12, v16, s27
	v_mad_u64_u32 v[16:17], s[8:9], v67, s25, v[80:81]
	ds_write_b16_d16_hi v16, v12
	v_mul_f32_e32 v12, v92, v13
	v_mul_f32_e32 v12, v95, v12
	v_cmp_ge_i32_e64 s[8:9], v66, v63
	s_nop 1
	v_cndmask_b32_e64 v12, 0, v12, s[8:9]
	v_bfe_u32 v13, v12, 16, 1
	v_add3_u32 v12, v12, v13, s27
	ds_write_b16_d16_hi v16, v12 offset:272
	v_mul_f32_e32 v12, v93, v14
	v_mul_f32_e32 v12, v95, v12
	v_cmp_ge_i32_e64 s[8:9], v65, v63
	s_nop 1
	v_cndmask_b32_e64 v12, 0, v12, s[8:9]
	v_bfe_u32 v13, v12, 16, 1
	v_add3_u32 v12, v12, v13, s27
	ds_write_b16_d16_hi v16, v12 offset:544
	v_mul_f32_e32 v12, v94, v15
	v_mul_f32_e32 v12, v95, v12
	v_cmp_ge_i32_e64 s[8:9], v64, v63
	s_nop 1
	v_cndmask_b32_e64 v12, 0, v12, s[8:9]
	v_bfe_u32 v13, v12, 16, 1
	v_add3_u32 v12, v12, v13, s27
	ds_write_b16_d16_hi v16, v12 offset:816
	v_bfe_u32 v12, v8, 16, 1
	v_add3_u32 v8, v8, v12, s27
	ds_write_b16_d16_hi v16, v8 offset:32
	v_mul_f32_e32 v8, v92, v9
	v_mul_f32_e32 v8, v96, v8
	v_cndmask_b32_e32 v8, 0, v8, vcc
	v_bfe_u32 v9, v8, 16, 1
	v_add3_u32 v8, v8, v9, s27
	ds_write_b16_d16_hi v16, v8 offset:304
	v_mul_f32_e32 v8, v93, v10
	v_mul_f32_e32 v8, v96, v8
	v_cmp_ge_i32_e32 vcc, v65, v116
	s_ashr_i32 s9, s30, 31
	s_sub_i32 s8, s30, 29
	v_cndmask_b32_e32 v8, 0, v8, vcc
	v_bfe_u32 v9, v8, 16, 1
	v_add3_u32 v8, v8, v9, s27
	ds_write_b16_d16_hi v16, v8 offset:576
	v_mul_f32_e32 v8, v94, v11
	v_mul_f32_e32 v8, v96, v8
	v_cmp_ge_i32_e32 vcc, v64, v116
	s_cmp_lt_i32 s30, 29
	s_cselect_b32 s31, s28, 0x1444800
	v_cndmask_b32_e32 v8, 0, v8, vcc
	v_bfe_u32 v9, v8, 16, 1
	v_cmp_ge_i32_e32 vcc, v67, v117
	v_add3_u32 v8, v8, v9, s27
	ds_write_b16_d16_hi v16, v8 offset:848
	v_cndmask_b32_e32 v4, 0, v4, vcc
	v_bfe_u32 v8, v4, 16, 1
	v_add3_u32 v4, v4, v8, s27
; __device__ __forceinline__ int fresh_tid(int wv) { int l; asm volatile("v_mbcnt_lo_u32_b32 %0, -1, 0\n\tv_mbcnt_hi_u32_b32 %0, -1, %0" : "=v"(l)); return wv * 64 + l; }
; #define LAS __attribute__((address_space(3)))
; template <bool WITH_K>
; __device__ __forceinline__ void ret_load_qk(PR P, LAS bf16_t* QP, LAS bf16_t* KB, unsigned (&kth)[4][4], const int tidv, const int row0, const int n, const int h, const float kd0, const float g32) {
;     ...
;             kth[it][0] = pg8::cvt_pk_bf16(ko1[0] * kd, ko1[1] * kd); kth[it][1] = pg8::cvt_pk_bf16(ko1[2] * kd, ko1[3] * kd);
;             kth[it][2] = pg8::cvt_pk_bf16(ko2[0] * kd, ko2[1] * kd); kth[it][3] = pg8::cvt_pk_bf16(ko2[2] * kd, ko2[3] * kd); kd *= g32; }
;         if (it & 1) __builtin_amdgcn_sched_barrier(0); }
; }
; __device__ __forceinline__ void ret_unit_a(PR P, LAS unsigned char* lds, const int bh, const int n, const int wv) {
;     LAS bf16_t* QP = (LAS bf16_t*)lds; LAS bf16_t* KB = QP + BUFE; LAS bf16_t* VT = KB + BUFE;
;     const int tid = fresh_tid(wv), lane = tid & 63, wid = tid >> 6, wr = wid >> 1, wc = wid & 1, fr = lane & 15, fq = lane >> 4;
;     const int b = bh >> 2, h = bh & 3;
;     const bf16_t* PS = (const bf16_t*)(P.ws + WS_BIG); bf16_t* Y = (bf16_t*)(P.ws + WS_XN); bf16_t* KVB = kvb_ptr(P.ws, bh) + (size_t)n * 16384;
;     const float lg2 = log2f(1.0f - exp2f(-5.0f - (float)h));
;     const float kd0 = exp2f(lg2 * (float)(127 - (tid >> 4))), g32 = exp2f(-32.0f * lg2);
;     ...
;       for (int mt = 0; mt < 2; ++mt)
; #pragma unroll
;           for (int nt = 0; nt < 4; ++nt)
; #pragma unroll
;               for (int j = 0; j < 4; ++j) { const int i = wr * 32 + mt * 16 + fq * 4 + j, jj = wc * 64 + nt * 16 + fr;
;                   const float val = i >= jj ? accP[mt][nt][j] * ri[mt][j] * cj[nt] : 0.f; QP[i * RS + jj] = f2bf(val); } }
; #pragma unroll
;     for (int it = 0; it < 4; ++it) { const int idx = it * 512 + tid, j = idx >> 4, f = (idx & 15) * 4; LAS bf16_t* d = KB + f * RS + j;
;         d[0] = (bf16_t)(kth[it][0] & 0xffffu); d[RS] = (bf16_t)(kth[it][0] >> 16); d[2 * RS] = (bf16_t)(kth[it][1] & 0xffffu); d[3 * RS] = (bf16_t)(kth[it][1] >> 16);
;         LAS bf16_t* d2 = d + 64 * RS;
;         d2[0] = (bf16_t)(kth[it][2] & 0xffffu); d2[RS] = (bf16_t)(kth[it][2] >> 16); d2[2 * RS] = (bf16_t)(kth[it][3] & 0xffffu); d2[3 * RS] = (bf16_t)(kth[it][3] >> 16); }
;     __syncthreads();
	ds_write_b16_d16_hi v16, v4 offset:64
	v_mul_f32_e32 v4, v92, v5
	v_mul_f32_e32 v4, v97, v4
	v_cmp_ge_i32_e32 vcc, v66, v117
	s_cselect_b32 s8, s30, s8
	s_cselect_b32 s9, s9, 0
	v_cndmask_b32_e32 v4, 0, v4, vcc
	v_bfe_u32 v5, v4, 16, 1
	v_add3_u32 v4, v4, v5, s27
	ds_write_b16_d16_hi v16, v4 offset:336
	v_mul_f32_e32 v4, v93, v6
	v_mul_f32_e32 v4, v97, v4
	v_cmp_ge_i32_e32 vcc, v65, v117
	s_add_u32 s30, s10, s31
	s_addc_u32 s31, s11, 0
	v_cndmask_b32_e32 v4, 0, v4, vcc
	v_bfe_u32 v5, v4, 16, 1
	v_add3_u32 v4, v4, v5, s27
	ds_write_b16_d16_hi v16, v4 offset:608
	v_mul_f32_e32 v4, v94, v7
	v_mul_f32_e32 v4, v97, v4
	v_cmp_ge_i32_e32 vcc, v64, v117
	s_lshl_b64 s[8:9], s[8:9], 19
	s_add_u32 s8, s30, s8
	v_cndmask_b32_e32 v4, 0, v4, vcc
	v_bfe_u32 v5, v4, 16, 1
	v_cmp_ge_i32_e32 vcc, v67, v118
	v_add3_u32 v4, v4, v5, s27
	ds_write_b16_d16_hi v16, v4 offset:880
	v_cndmask_b32_e32 v0, 0, v0, vcc
	v_bfe_u32 v4, v0, 16, 1
	v_add3_u32 v0, v0, v4, s27
	ds_write_b16_d16_hi v16, v0 offset:96
	v_mul_f32_e32 v0, v92, v1
	v_mul_f32_e32 v0, v98, v0
	v_cmp_ge_i32_e32 vcc, v66, v118
	s_addc_u32 s9, s31, s9
	s_add_u32 s8, s8, s7
	v_cndmask_b32_e32 v0, 0, v0, vcc
	v_bfe_u32 v1, v0, 16, 1
	v_add3_u32 v0, v0, v1, s27
	ds_write_b16_d16_hi v16, v0 offset:368
	v_mul_f32_e32 v0, v93, v2
	v_mul_f32_e32 v0, v98, v0
	v_cmp_ge_i32_e32 vcc, v65, v118
	s_addc_u32 s9, s9, 0
	s_nop 0
	v_cndmask_b32_e32 v0, 0, v0, vcc
	v_bfe_u32 v1, v0, 16, 1
	v_add3_u32 v0, v0, v1, s27
	ds_write_b16_d16_hi v16, v0 offset:640
	v_mul_f32_e32 v0, v94, v3
	v_mul_f32_e32 v0, v98, v0
	v_cmp_ge_i32_e32 vcc, v64, v118
	s_nop 1
	v_cndmask_b32_e32 v4, 0, v0, vcc
	v_sub_u32_e32 v0, 0x7f, v61
	v_cvt_f32_i32_e32 v0, v0
	v_mul_f32_e32 v1, v62, v0
	v_cmp_gt_f32_e32 vcc, s21, v1
	s_nop 1
	v_cndmask_b32_e32 v1, 0, v56, vcc
	v_fmac_f32_e32 v1, v62, v0
	v_exp_f32_e32 v0, v1
	v_cndmask_b32_e32 v1, 0, v59, vcc
	v_ldexp_f32 v0, v0, v1
	v_pk_mul_f32 v[2:3], v[0:1], v[22:23] op_sel_hi:[0,1]
	v_cvt_pk_bf16_f32 v5, v2, v3
	v_pk_mul_f32 v[2:3], v[0:1], v[26:27] op_sel_hi:[0,1]
	v_cvt_pk_bf16_f32 v6, v2, v3
	v_pk_mul_f32 v[2:3], v[0:1], v[20:21] op_sel_hi:[0,1]
	v_cvt_pk_bf16_f32 v7, v2, v3
	v_pk_mul_f32 v[2:3], v[0:1], v[24:25] op_sel_hi:[0,1]
	v_mul_f32_e32 v1, 0xc2000000, v62
	v_cmp_gt_f32_e32 vcc, s21, v1
	s_and_b64 s[30:31], vcc, exec
	s_cselect_b32 s30, 0xffffffc0, 0
	v_cndmask_b32_e32 v1, 0, v56, vcc
	v_fmac_f32_e32 v1, 0xc2000000, v62
	v_exp_f32_e32 v1, v1
	v_cvt_pk_bf16_f32 v8, v2, v3
	v_ldexp_f32 v1, v1, s30
	v_mul_f32_e32 v0, v1, v0
	v_pk_mul_f32 v[2:3], v[0:1], v[34:35] op_sel_hi:[0,1]
	v_cvt_pk_bf16_f32 v9, v2, v3
	v_pk_mul_f32 v[2:3], v[0:1], v[38:39] op_sel_hi:[0,1]
	v_cvt_pk_bf16_f32 v10, v2, v3
	v_pk_mul_f32 v[2:3], v[0:1], v[32:33] op_sel_hi:[0,1]
	v_cvt_pk_bf16_f32 v11, v2, v3
	v_pk_mul_f32 v[2:3], v[0:1], v[36:37] op_sel_hi:[0,1]
	v_mul_f32_e32 v0, v1, v0
	v_cvt_pk_bf16_f32 v12, v2, v3
	v_pk_mul_f32 v[2:3], v[0:1], v[44:45] op_sel_hi:[0,1]
	v_cvt_pk_bf16_f32 v13, v2, v3
	v_pk_mul_f32 v[2:3], v[0:1], v[46:47] op_sel_hi:[0,1]
	v_cvt_pk_bf16_f32 v14, v2, v3
	v_pk_mul_f32 v[2:3], v[0:1], v[40:41] op_sel_hi:[0,1]
	v_cvt_pk_bf16_f32 v15, v2, v3
	v_pk_mul_f32 v[2:3], v[0:1], v[42:43] op_sel_hi:[0,1]
	v_mul_f32_e32 v0, v1, v0
	v_cvt_pk_bf16_f32 v17, v2, v3
	v_pk_mul_f32 v[2:3], v[0:1], v[50:51] op_sel_hi:[0,1]
	v_cvt_pk_bf16_f32 v18, v2, v3
	v_pk_mul_f32 v[2:3], v[0:1], v[54:55] op_sel_hi:[0,1]
	v_cvt_pk_bf16_f32 v19, v2, v3
	v_pk_mul_f32 v[2:3], v[0:1], v[48:49] op_sel_hi:[0,1]
	v_pk_mul_f32 v[0:1], v[0:1], v[52:53] op_sel_hi:[0,1]
	v_cvt_pk_bf16_f32 v0, v0, v1
	v_bfe_u32 v1, v4, 16, 1
	v_add3_u32 v1, v4, v1, s27
	ds_write_b16_d16_hi v16, v1 offset:912
	v_mad_u32_u24 v1, v60, s25, 0
	v_cvt_pk_bf16_f32 v2, v2, v3
	v_add_u32_e32 v3, v1, v79
	ds_write_b16 v3, v5 offset:34816
	ds_write_b16_d16_hi v3, v5 offset:35088
	ds_write_b16 v3, v6 offset:35360
	ds_write_b16_d16_hi v3, v6 offset:35632
	ds_write_b16 v3, v7 offset:52224
	ds_write_b16_d16_hi v3, v7 offset:52496
	ds_write_b16 v3, v8 offset:52768
	ds_write_b16_d16_hi v3, v8 offset:53040
	v_add_u32_e32 v3, v1, v78
	ds_write_b16 v3, v9 offset:34816
	ds_write_b16_d16_hi v3, v9 offset:35088
	ds_write_b16 v3, v10 offset:35360
	ds_write_b16_d16_hi v3, v10 offset:35632
	ds_write_b16 v3, v11 offset:52224
	ds_write_b16_d16_hi v3, v11 offset:52496
	ds_write_b16 v3, v12 offset:52768
	ds_write_b16_d16_hi v3, v12 offset:53040
	v_add_u32_e32 v3, v1, v76
	v_add_u32_e32 v1, v1, v74
	ds_write_b16 v3, v13 offset:34816
	ds_write_b16_d16_hi v3, v13 offset:35088
	ds_write_b16 v3, v14 offset:35360
	ds_write_b16_d16_hi v3, v14 offset:35632
	ds_write_b16 v3, v15 offset:52224
	ds_write_b16_d16_hi v3, v15 offset:52496
	ds_write_b16 v3, v17 offset:52768
	ds_write_b16_d16_hi v3, v17 offset:53040
	ds_write_b16 v1, v18 offset:34816
	ds_write_b16_d16_hi v1, v18 offset:35088
	ds_write_b16 v1, v19 offset:35360
	ds_write_b16_d16_hi v1, v19 offset:35632
	ds_write_b16 v1, v2 offset:52224
	ds_write_b16_d16_hi v1, v2 offset:52496
	ds_write_b16 v1, v0 offset:52768
	ds_write_b16_d16_hi v1, v0 offset:53040
	s_waitcnt lgkmcnt(0)
	s_barrier
; #define LAS __attribute__((address_space(3)))
; __device__ __forceinline__ void ret_unit_a(PR P, LAS unsigned char* lds, const int bh, const int n, const int wv) {
;     ...
;     for (int ks = 0; ks < 4; ++ks) { bf16x8 ap[2], av[2];
; #pragma unroll
;         for (int mt = 0; mt < 2; ++mt) { ap[mt] = *(const LAS bf16x8*)(QP + (wr * 32 + mt * 16 + fr) * RS + ks * 32 + fq * 8); av[mt] = *(const LAS bf16x8*)(VT + (wr * 32 + mt * 16 + fr) * RS + ks * 32 + fq * 8); }
; #pragma unroll
;         for (int nt = 0; nt < 4; ++nt) { const bf16x8 bv = *(const LAS bf16x8*)(VT + (wc * 64 + nt * 16 + fr) * RS + ks * 32 + fq * 8), bkt = *(const LAS bf16x8*)(KB + (wc * 64 + nt * 16 + fr) * RS + ks * 32 + fq * 8);
; #pragma unroll
;             for (int mt = 0; mt < 2; ++mt) { accY[mt][nt] = __builtin_amdgcn_mfma_f32_16x16x32_bf16(ap[mt], bv, accY[mt][nt], 0, 0, 0); accS[mt][nt] = __builtin_amdgcn_mfma_f32_16x16x32_bf16(av[mt], bkt, accS[mt][nt], 0, 0, 0); } }
;         __builtin_amdgcn_sched_barrier(0); }
	ds_read_b128 v[0:3], v68
	v_mul_u32_u24_e32 v5, 0x88, v63
	v_add_u32_e32 v4, s26, v75
	v_lshlrev_b32_e32 v16, 1, v5
	v_add_u32_e32 v61, v4, v16
	v_add_u32_e32 v62, v73, v16
	v_add_u32_e32 v60, v4, v77
	ds_read_b128 v[4:7], v61
	ds_read_b128 v[8:11], v60
	ds_read_b128 v[12:15], v68 offset:4352
	ds_read_b128 v[16:19], v61 offset:4352
	ds_read_b128 v[24:27], v62 offset:34816
	ds_read_b128 v[32:35], v60 offset:4352
	ds_read_b128 v[36:39], v62 offset:39168
	ds_read_b128 v[52:55], v61 offset:8704
	ds_read_b128 v[74:77], v61 offset:13056
	ds_read_b128 v[82:85], v62 offset:43520
	ds_read_b128 v[86:89], v62 offset:47872
	s_waitcnt lgkmcnt(10)
	v_mfma_f32_16x16x32_bf16 v[20:23], v[0:3], v[4:7], 0
	s_waitcnt lgkmcnt(6)
	v_mfma_f32_16x16x32_bf16 v[40:43], v[8:11], v[24:27], 0
	v_mfma_f32_16x16x32_bf16 v[4:7], v[12:15], v[4:7], 0
	s_waitcnt lgkmcnt(5)
	v_mfma_f32_16x16x32_bf16 v[24:27], v[32:35], v[24:27], 0
	v_mfma_f32_16x16x32_bf16 v[44:47], v[0:3], v[16:19], 0
	s_waitcnt lgkmcnt(4)
	v_mfma_f32_16x16x32_bf16 v[48:51], v[8:11], v[36:39], 0
	v_mfma_f32_16x16x32_bf16 v[16:19], v[12:15], v[16:19], 0
	v_mfma_f32_16x16x32_bf16 v[36:39], v[32:35], v[36:39], 0
	s_waitcnt lgkmcnt(3)
	v_mfma_f32_16x16x32_bf16 v[78:81], v[0:3], v[52:55], 0
	s_waitcnt lgkmcnt(1)
	v_mfma_f32_16x16x32_bf16 v[90:93], v[8:11], v[82:85], 0
	v_mfma_f32_16x16x32_bf16 v[52:55], v[12:15], v[52:55], 0
	v_mfma_f32_16x16x32_bf16 v[82:85], v[32:35], v[82:85], 0
	v_mfma_f32_16x16x32_bf16 v[0:3], v[0:3], v[74:77], 0
	s_waitcnt lgkmcnt(0)
	v_mfma_f32_16x16x32_bf16 v[8:11], v[8:11], v[86:89], 0
	v_mfma_f32_16x16x32_bf16 v[12:15], v[12:15], v[74:77], 0
	v_mfma_f32_16x16x32_bf16 v[32:35], v[32:35], v[86:89], 0
	ds_read_b128 v[74:77], v68 offset:64
	ds_read_b128 v[86:89], v61 offset:64
	ds_read_b128 v[94:97], v60 offset:64
	ds_read_b128 v[98:101], v68 offset:4416
	ds_read_b128 v[102:105], v61 offset:4416
	ds_read_b128 v[106:109], v62 offset:34880
	ds_read_b128 v[110:113], v60 offset:4416
	ds_read_b128 v[114:117], v62 offset:39232
	s_waitcnt lgkmcnt(6)
	v_mfma_f32_16x16x32_bf16 v[20:23], v[74:77], v[86:89], v[20:23]
	s_waitcnt lgkmcnt(2)
	v_mfma_f32_16x16x32_bf16 v[40:43], v[94:97], v[106:109], v[40:43]
	v_mfma_f32_16x16x32_bf16 v[4:7], v[98:101], v[86:89], v[4:7]
	s_waitcnt lgkmcnt(1)
	v_mfma_f32_16x16x32_bf16 v[24:27], v[110:113], v[106:109], v[24:27]
	v_mfma_f32_16x16x32_bf16 v[44:47], v[74:77], v[102:105], v[44:47]
	s_waitcnt lgkmcnt(0)
	v_mfma_f32_16x16x32_bf16 v[48:51], v[94:97], v[114:117], v[48:51]
	v_mfma_f32_16x16x32_bf16 v[16:19], v[98:101], v[102:105], v[16:19]
	ds_read_b128 v[86:89], v61 offset:8768
	ds_read_b128 v[102:105], v61 offset:13120
	v_mfma_f32_16x16x32_bf16 v[36:39], v[110:113], v[114:117], v[36:39]
	ds_read_b128 v[106:109], v62 offset:43584
	ds_read_b128 v[114:117], v62 offset:47936
	s_waitcnt lgkmcnt(3)
	v_mfma_f32_16x16x32_bf16 v[78:81], v[74:77], v[86:89], v[78:81]
	s_waitcnt lgkmcnt(1)
	v_mfma_f32_16x16x32_bf16 v[90:93], v[94:97], v[106:109], v[90:93]
	v_mfma_f32_16x16x32_bf16 v[52:55], v[98:101], v[86:89], v[52:55]
	v_mfma_f32_16x16x32_bf16 v[82:85], v[110:113], v[106:109], v[82:85]
	v_mfma_f32_16x16x32_bf16 v[0:3], v[74:77], v[102:105], v[0:3]
	s_waitcnt lgkmcnt(0)
	v_mfma_f32_16x16x32_bf16 v[8:11], v[94:97], v[114:117], v[8:11]
	v_mfma_f32_16x16x32_bf16 v[12:15], v[98:101], v[102:105], v[12:15]
	v_mfma_f32_16x16x32_bf16 v[32:35], v[110:113], v[114:117], v[32:35]
	ds_read_b128 v[74:77], v68 offset:128
	ds_read_b128 v[86:89], v61 offset:128
	ds_read_b128 v[94:97], v60 offset:128
	ds_read_b128 v[98:101], v68 offset:4480
	ds_read_b128 v[102:105], v61 offset:4480
	ds_read_b128 v[106:109], v62 offset:34944
	ds_read_b128 v[110:113], v60 offset:4480
	ds_read_b128 v[114:117], v62 offset:39296
	s_waitcnt lgkmcnt(6)
	v_mfma_f32_16x16x32_bf16 v[20:23], v[74:77], v[86:89], v[20:23]
	s_waitcnt lgkmcnt(2)
	v_mfma_f32_16x16x32_bf16 v[40:43], v[94:97], v[106:109], v[40:43]
	v_mfma_f32_16x16x32_bf16 v[4:7], v[98:101], v[86:89], v[4:7]
	s_waitcnt lgkmcnt(1)
	v_mfma_f32_16x16x32_bf16 v[24:27], v[110:113], v[106:109], v[24:27]
	v_mfma_f32_16x16x32_bf16 v[44:47], v[74:77], v[102:105], v[44:47]
	s_waitcnt lgkmcnt(0)
	v_mfma_f32_16x16x32_bf16 v[48:51], v[94:97], v[114:117], v[48:51]
	v_mfma_f32_16x16x32_bf16 v[16:19], v[98:101], v[102:105], v[16:19]
	ds_read_b128 v[86:89], v61 offset:8832
	ds_read_b128 v[102:105], v61 offset:13184
	v_mfma_f32_16x16x32_bf16 v[36:39], v[110:113], v[114:117], v[36:39]
	ds_read_b128 v[106:109], v62 offset:43648
	ds_read_b128 v[114:117], v62 offset:48000
	s_waitcnt lgkmcnt(3)
	v_mfma_f32_16x16x32_bf16 v[78:81], v[74:77], v[86:89], v[78:81]
	s_waitcnt lgkmcnt(1)
	v_mfma_f32_16x16x32_bf16 v[90:93], v[94:97], v[106:109], v[90:93]
	v_mfma_f32_16x16x32_bf16 v[52:55], v[98:101], v[86:89], v[52:55]
	v_mfma_f32_16x16x32_bf16 v[82:85], v[110:113], v[106:109], v[82:85]
	v_mfma_f32_16x16x32_bf16 v[0:3], v[74:77], v[102:105], v[0:3]
	s_waitcnt lgkmcnt(0)
	v_mfma_f32_16x16x32_bf16 v[74:77], v[94:97], v[114:117], v[8:11]
	v_mfma_f32_16x16x32_bf16 v[86:89], v[98:101], v[102:105], v[12:15]
	v_mfma_f32_16x16x32_bf16 v[32:35], v[110:113], v[114:117], v[32:35]
	ds_read_b128 v[94:97], v68 offset:192
	ds_read_b128 v[8:11], v61 offset:192
	ds_read_b128 v[98:101], v60 offset:192
	ds_read_b128 v[102:105], v68 offset:4544
	ds_read_b128 v[12:15], v61 offset:4544
	s_waitcnt lgkmcnt(3)
	v_mfma_f32_16x16x32_bf16 v[106:109], v[94:97], v[8:11], v[20:23]
	s_nop 2
	ds_read_b128 v[20:23], v62 offset:35008
	ds_read_b128 v[110:113], v60 offset:4544
	ds_read_b128 v[114:117], v62 offset:39360
	s_waitcnt lgkmcnt(2)
	v_mfma_f32_16x16x32_bf16 v[40:43], v[98:101], v[20:23], v[40:43]
	v_mfma_f32_16x16x32_bf16 v[118:121], v[102:105], v[8:11], v[4:7]
	s_waitcnt lgkmcnt(1)
; #define LAS __attribute__((address_space(3)))
; __device__ __forceinline__ bf16_t f2bf(float f) { unsigned u = __float_as_uint(f); u += 0x7FFFu + ((u >> 16) & 1u); return (bf16_t)(u >> 16); }
; __device__ __forceinline__ void ret_unit_a(PR P, LAS unsigned char* lds, const int bh, const int n, const int wv) {
;     ...
;     for (int ks = 0; ks < 4; ++ks) { bf16x8 ap[2], av[2];
; #pragma unroll
;         for (int mt = 0; mt < 2; ++mt) { ap[mt] = *(const LAS bf16x8*)(QP + (wr * 32 + mt * 16 + fr) * RS + ks * 32 + fq * 8); av[mt] = *(const LAS bf16x8*)(VT + (wr * 32 + mt * 16 + fr) * RS + ks * 32 + fq * 8); }
; #pragma unroll
;         for (int nt = 0; nt < 4; ++nt) { const bf16x8 bv = *(const LAS bf16x8*)(VT + (wc * 64 + nt * 16 + fr) * RS + ks * 32 + fq * 8), bkt = *(const LAS bf16x8*)(KB + (wc * 64 + nt * 16 + fr) * RS + ks * 32 + fq * 8);
; #pragma unroll
;             for (int mt = 0; mt < 2; ++mt) { accY[mt][nt] = __builtin_amdgcn_mfma_f32_16x16x32_bf16(ap[mt], bv, accY[mt][nt], 0, 0, 0); accS[mt][nt] = __builtin_amdgcn_mfma_f32_16x16x32_bf16(av[mt], bkt, accS[mt][nt], 0, 0, 0); } }
;         __builtin_amdgcn_sched_barrier(0); }
; #pragma unroll
;     for (int mt = 0; mt < 2; ++mt)
; #pragma unroll
;         for (int nt = 0; nt < 4; ++nt)
; #pragma unroll
;             for (int j = 0; j < 4; ++j) { const int r = wr * 32 + mt * 16 + fq * 4 + j, c = wc * 64 + nt * 16 + fr;
;                 Y[(size_t)(row0 + r) * 1024 + 512 + h * 128 + c] = f2bf(accY[mt][nt][j]); KVB[r * 128 + c] = f2bf(accS[mt][nt][j]); }
	v_mfma_f32_16x16x32_bf16 v[24:27], v[110:113], v[20:23], v[24:27]
	s_waitcnt lgkmcnt(0)
	v_mfma_f32_16x16x32_bf16 v[48:51], v[98:101], v[114:117], v[48:51]
	v_mfma_f32_16x16x32_bf16 v[20:23], v[102:105], v[12:15], v[16:19]
	v_mfma_f32_16x16x32_bf16 v[16:19], v[110:113], v[114:117], v[36:39]
	ds_read_b128 v[4:7], v61 offset:8896
	s_nop 1
	ds_read_b128 v[36:39], v61 offset:13248
	ds_read_b128 v[8:11], v62 offset:43712
	ds_read_b128 v[114:117], v62 offset:48064
	v_mfma_f32_16x16x32_bf16 v[44:47], v[94:97], v[12:15], v[44:47]
	s_waitcnt lgkmcnt(3)
	v_mfma_f32_16x16x32_bf16 v[78:81], v[94:97], v[4:7], v[78:81]
	s_waitcnt lgkmcnt(1)
	v_mfma_f32_16x16x32_bf16 v[90:93], v[98:101], v[8:11], v[90:93]
	v_mfma_f32_16x16x32_bf16 v[12:15], v[102:105], v[4:7], v[52:55]
	v_mfma_f32_16x16x32_bf16 v[8:11], v[110:113], v[8:11], v[82:85]
	v_mfma_f32_16x16x32_bf16 v[52:55], v[94:97], v[36:39], v[0:3]
	s_waitcnt lgkmcnt(0)
	v_mfma_f32_16x16x32_bf16 v[74:77], v[98:101], v[114:117], v[74:77]
	v_mfma_f32_16x16x32_bf16 v[4:7], v[102:105], v[36:39], v[86:89]
	v_mfma_f32_16x16x32_bf16 v[0:3], v[110:113], v[114:117], v[32:35]
	s_add_u32 s30, s4, s12
	s_nop 1
	v_add_u32_e32 v34, s29, v72
	s_addc_u32 s31, s5, 0
	v_ashrrev_i32_e32 v35, 31, v34
	v_lshl_add_u64 v[32:33], s[30:31], 0, v[28:29]
	v_bfe_u32 v28, v106, 16, 1
	v_lshlrev_b64 v[34:35], 11, v[34:35]
	v_lshlrev_b32_e32 v62, 7, v72
	v_add3_u32 v28, v106, v28, s27
	v_lshl_add_u64 v[34:35], v[32:33], 0, v[34:35]
	v_or_b32_e32 v36, v62, v63
	global_store_short_d16_hi v[34:35], v28, off
	v_bfe_u32 v28, v40, 16, 1
	v_ashrrev_i32_e32 v37, 31, v36
	v_add3_u32 v28, v40, v28, s27
	v_lshl_add_u64 v[38:39], v[36:37], 1, s[8:9]
	global_store_short_d16_hi v[38:39], v28, off
	v_add_u32_e32 v38, s29, v71
	v_ashrrev_i32_e32 v39, 31, v38
	v_bfe_u32 v28, v107, 16, 1
	v_lshlrev_b64 v[38:39], 11, v[38:39]
	v_add3_u32 v28, v107, v28, s27
	v_lshl_add_u64 v[38:39], v[32:33], 0, v[38:39]
	v_lshlrev_b32_e32 v82, 7, v71
	global_store_short_d16_hi v[38:39], v28, off
	v_bfe_u32 v28, v41, 16, 1
	v_or_b32_e32 v40, v82, v63
	v_add3_u32 v28, v41, v28, s27
	v_ashrrev_i32_e32 v41, 31, v40
	v_lshl_add_u64 v[60:61], v[40:41], 1, s[8:9]
	global_store_short_d16_hi v[60:61], v28, off
	v_add_u32_e32 v60, s29, v70
	v_ashrrev_i32_e32 v61, 31, v60
	v_bfe_u32 v28, v108, 16, 1
	v_lshlrev_b64 v[60:61], 11, v[60:61]
	v_lshlrev_b32_e32 v83, 7, v70
	v_add3_u32 v28, v108, v28, s27
	v_lshl_add_u64 v[60:61], v[32:33], 0, v[60:61]
	v_or_b32_e32 v70, v83, v63
	global_store_short_d16_hi v[60:61], v28, off
	v_bfe_u32 v28, v42, 16, 1
	v_ashrrev_i32_e32 v71, 31, v70
	v_add3_u32 v28, v42, v28, s27
	v_lshl_add_u64 v[72:73], v[70:71], 1, s[8:9]
	global_store_short_d16_hi v[72:73], v28, off
	v_add_u32_e32 v72, s29, v69
	v_ashrrev_i32_e32 v73, 31, v72
	v_bfe_u32 v28, v109, 16, 1
	v_lshlrev_b64 v[72:73], 11, v[72:73]
	v_add3_u32 v28, v109, v28, s27
	v_lshl_add_u64 v[72:73], v[32:33], 0, v[72:73]
	v_lshlrev_b32_e32 v84, 7, v69
	global_store_short_d16_hi v[72:73], v28, off
	v_bfe_u32 v28, v43, 16, 1
	v_or_b32_e32 v42, v84, v63
	v_add3_u32 v28, v43, v28, s27
	v_ashrrev_i32_e32 v43, 31, v42
	v_lshl_add_u64 v[68:69], v[42:43], 1, s[8:9]
	global_store_short_d16_hi v[68:69], v28, off
	v_bfe_u32 v28, v44, 16, 1
	v_add3_u32 v28, v44, v28, s27
	global_store_short_d16_hi v[34:35], v28, off offset:32
	v_bfe_u32 v28, v48, 16, 1
	v_ashrrev_i32_e32 v37, 31, v62
	v_add3_u32 v28, v48, v28, s27
	v_lshl_add_u64 v[36:37], v[36:37], 1, s[8:9]
	global_store_short_d16_hi v[36:37], v28, off offset:32
	v_bfe_u32 v28, v45, 16, 1
	v_add3_u32 v28, v45, v28, s27
	global_store_short_d16_hi v[38:39], v28, off offset:32
	v_bfe_u32 v28, v49, 16, 1
	v_ashrrev_i32_e32 v41, 31, v82
	v_add3_u32 v28, v49, v28, s27
	v_lshl_add_u64 v[40:41], v[40:41], 1, s[8:9]
	global_store_short_d16_hi v[40:41], v28, off offset:32
	v_bfe_u32 v28, v46, 16, 1
	v_add3_u32 v28, v46, v28, s27
	global_store_short_d16_hi v[60:61], v28, off offset:32
	v_bfe_u32 v28, v50, 16, 1
	v_ashrrev_i32_e32 v71, 31, v83
	v_add3_u32 v28, v50, v28, s27
	v_lshl_add_u64 v[44:45], v[70:71], 1, s[8:9]
	global_store_short_d16_hi v[44:45], v28, off offset:32
	v_bfe_u32 v28, v47, 16, 1
	v_add3_u32 v28, v47, v28, s27
	global_store_short_d16_hi v[72:73], v28, off offset:32
	v_bfe_u32 v28, v51, 16, 1
	v_ashrrev_i32_e32 v43, 31, v84
	v_add3_u32 v28, v51, v28, s27
	v_lshl_add_u64 v[42:43], v[42:43], 1, s[8:9]
	global_store_short_d16_hi v[42:43], v28, off offset:32
	v_bfe_u32 v28, v78, 16, 1
	v_add3_u32 v28, v78, v28, s27
	global_store_short_d16_hi v[34:35], v28, off offset:64
	v_bfe_u32 v28, v90, 16, 1
	v_add3_u32 v28, v90, v28, s27
	global_store_short_d16_hi v[36:37], v28, off offset:64
	v_bfe_u32 v28, v79, 16, 1
	v_add3_u32 v28, v79, v28, s27
	global_store_short_d16_hi v[38:39], v28, off offset:64
	v_bfe_u32 v28, v91, 16, 1
	v_add3_u32 v28, v91, v28, s27
	global_store_short_d16_hi v[40:41], v28, off offset:64
	v_bfe_u32 v28, v80, 16, 1
	v_add3_u32 v28, v80, v28, s27
	global_store_short_d16_hi v[60:61], v28, off offset:64
	v_bfe_u32 v28, v92, 16, 1
	v_add3_u32 v28, v92, v28, s27
	global_store_short_d16_hi v[44:45], v28, off offset:64
	v_bfe_u32 v28, v81, 16, 1
	v_add3_u32 v28, v81, v28, s27
	global_store_short_d16_hi v[72:73], v28, off offset:64
	v_bfe_u32 v28, v93, 16, 1
	v_add3_u32 v28, v93, v28, s27
	global_store_short_d16_hi v[42:43], v28, off offset:64
	v_bfe_u32 v28, v52, 16, 1
	v_add3_u32 v28, v52, v28, s27
	global_store_short_d16_hi v[34:35], v28, off offset:96
	v_bfe_u32 v28, v74, 16, 1
	v_add3_u32 v28, v74, v28, s27
	global_store_short_d16_hi v[36:37], v28, off offset:96
	v_bfe_u32 v28, v53, 16, 1
	v_add3_u32 v28, v53, v28, s27
; __device__ __forceinline__ int fresh_tid(int wv) { int l; asm volatile("v_mbcnt_lo_u32_b32 %0, -1, 0\n\tv_mbcnt_hi_u32_b32 %0, -1, %0" : "=v"(l)); return wv * 64 + l; }
; __device__ __forceinline__ bf16_t f2bf(float f) { unsigned u = __float_as_uint(f); u += 0x7FFFu + ((u >> 16) & 1u); return (bf16_t)(u >> 16); }
; __device__ __forceinline__ unsigned xb_add(unsigned* p, unsigned v) { return __hip_atomic_fetch_add(p, v, __ATOMIC_RELAXED, __HIP_MEMORY_SCOPE_AGENT); }
; __device__ __forceinline__ void ret_unit_a(PR P, LAS unsigned char* lds, const int bh, const int n, const int wv) {
;     ...
; #pragma unroll
;     for (int mt = 0; mt < 2; ++mt)
; #pragma unroll
;         for (int nt = 0; nt < 4; ++nt)
; #pragma unroll
;             for (int j = 0; j < 4; ++j) { const int r = wr * 32 + mt * 16 + fq * 4 + j, c = wc * 64 + nt * 16 + fr;
;                 Y[(size_t)(row0 + r) * 1024 + 512 + h * 128 + c] = f2bf(accY[mt][nt][j]); KVB[r * 128 + c] = f2bf(accS[mt][nt][j]); }
;     __syncthreads();
; __device__ __forceinline__ void sub_barrier(unsigned* cnt, const unsigned target, const int wv) {
;     asm volatile("s_waitcnt vmcnt(0)" ::: "memory");
;     __syncthreads();
;     if (fresh_tid(wv) == 0) {
;         __builtin_amdgcn_fence(__ATOMIC_RELEASE, "agent");
;         asm volatile("s_waitcnt vmcnt(0)" ::: "memory");
;         (void)xb_add(cnt, 1u);
	global_store_short_d16_hi v[38:39], v28, off offset:96
	v_bfe_u32 v28, v75, 16, 1
	v_add3_u32 v28, v75, v28, s27
	global_store_short_d16_hi v[40:41], v28, off offset:96
	v_bfe_u32 v28, v54, 16, 1
	v_add3_u32 v28, v54, v28, s27
	global_store_short_d16_hi v[60:61], v28, off offset:96
	v_bfe_u32 v28, v76, 16, 1
	v_add3_u32 v28, v76, v28, s27
	global_store_short_d16_hi v[44:45], v28, off offset:96
	v_bfe_u32 v28, v55, 16, 1
	v_add3_u32 v28, v55, v28, s27
	global_store_short_d16_hi v[72:73], v28, off offset:96
	v_bfe_u32 v28, v77, 16, 1
	v_add_u32_e32 v34, s29, v67
	v_add3_u32 v28, v77, v28, s27
	v_ashrrev_i32_e32 v35, 31, v34
	global_store_short_d16_hi v[42:43], v28, off offset:96
	v_bfe_u32 v28, v118, 16, 1
	v_lshlrev_b64 v[34:35], 11, v[34:35]
	v_add3_u32 v28, v118, v28, s27
	v_lshl_add_u64 v[34:35], v[32:33], 0, v[34:35]
	global_store_short_d16_hi v[34:35], v28, off
	v_bfe_u32 v28, v24, 16, 1
	v_add3_u32 v24, v24, v28, s27
	v_lshlrev_b32_e32 v28, 7, v67
	v_or_b32_e32 v36, v28, v63
	v_ashrrev_i32_e32 v37, 31, v36
	v_lshl_add_u64 v[38:39], v[36:37], 1, s[8:9]
	global_store_short_d16_hi v[38:39], v24, off
	v_add_u32_e32 v38, s29, v66
	v_ashrrev_i32_e32 v39, 31, v38
	v_bfe_u32 v24, v119, 16, 1
	v_lshlrev_b64 v[38:39], 11, v[38:39]
	v_add3_u32 v24, v119, v24, s27
	v_lshl_add_u64 v[38:39], v[32:33], 0, v[38:39]
	global_store_short_d16_hi v[38:39], v24, off
	v_bfe_u32 v24, v25, 16, 1
	v_lshlrev_b32_e32 v46, 7, v66
	v_add3_u32 v37, v25, v24, s27
	v_or_b32_e32 v24, v46, v63
	v_ashrrev_i32_e32 v25, 31, v24
	v_lshl_add_u64 v[40:41], v[24:25], 1, s[8:9]
	global_store_short_d16_hi v[40:41], v37, off
	v_add_u32_e32 v40, s29, v65
	v_ashrrev_i32_e32 v41, 31, v40
	v_bfe_u32 v25, v120, 16, 1
	v_lshlrev_b64 v[40:41], 11, v[40:41]
	v_lshlrev_b32_e32 v47, 7, v65
	v_add3_u32 v25, v120, v25, s27
	v_lshl_add_u64 v[40:41], v[32:33], 0, v[40:41]
	v_or_b32_e32 v42, v47, v63
	global_store_short_d16_hi v[40:41], v25, off
	v_bfe_u32 v25, v26, 16, 1
	v_ashrrev_i32_e32 v43, 31, v42
	v_add3_u32 v25, v26, v25, s27
	v_lshl_add_u64 v[44:45], v[42:43], 1, s[8:9]
	global_store_short_d16_hi v[44:45], v25, off
	v_add_u32_e32 v44, s29, v64
	v_ashrrev_i32_e32 v45, 31, v44
	v_bfe_u32 v25, v121, 16, 1
	v_lshlrev_b64 v[44:45], 11, v[44:45]
	v_add3_u32 v25, v121, v25, s27
	v_lshl_add_u64 v[32:33], v[32:33], 0, v[44:45]
	v_lshlrev_b32_e32 v48, 7, v64
	global_store_short_d16_hi v[32:33], v25, off
	v_bfe_u32 v25, v27, 16, 1
	v_or_b32_e32 v26, v48, v63
	v_add3_u32 v25, v27, v25, s27
	v_ashrrev_i32_e32 v27, 31, v26
	v_lshl_add_u64 v[44:45], v[26:27], 1, s[8:9]
	global_store_short_d16_hi v[44:45], v25, off
	v_bfe_u32 v25, v20, 16, 1
	v_add3_u32 v20, v20, v25, s27
	global_store_short_d16_hi v[34:35], v20, off offset:32
	v_bfe_u32 v20, v16, 16, 1
	v_ashrrev_i32_e32 v37, 31, v28
	v_add3_u32 v16, v16, v20, s27
	v_lshl_add_u64 v[36:37], v[36:37], 1, s[8:9]
	global_store_short_d16_hi v[36:37], v16, off offset:32
	v_bfe_u32 v16, v21, 16, 1
	v_add3_u32 v16, v21, v16, s27
	global_store_short_d16_hi v[38:39], v16, off offset:32
	v_bfe_u32 v16, v17, 16, 1
	v_ashrrev_i32_e32 v25, 31, v46
	v_add3_u32 v20, v17, v16, s27
	v_lshl_add_u64 v[16:17], v[24:25], 1, s[8:9]
	global_store_short_d16_hi v[16:17], v20, off offset:32
	v_bfe_u32 v20, v22, 16, 1
	v_add3_u32 v20, v22, v20, s27
	global_store_short_d16_hi v[40:41], v20, off offset:32
	v_bfe_u32 v20, v18, 16, 1
	v_ashrrev_i32_e32 v43, 31, v47
	v_add3_u32 v18, v18, v20, s27
	v_lshl_add_u64 v[20:21], v[42:43], 1, s[8:9]
	global_store_short_d16_hi v[20:21], v18, off offset:32
	v_bfe_u32 v18, v23, 16, 1
	v_add3_u32 v18, v23, v18, s27
	global_store_short_d16_hi v[32:33], v18, off offset:32
	v_bfe_u32 v18, v19, 16, 1
	v_ashrrev_i32_e32 v27, 31, v48
	v_add3_u32 v22, v19, v18, s27
	v_lshl_add_u64 v[18:19], v[26:27], 1, s[8:9]
	global_store_short_d16_hi v[18:19], v22, off offset:32
	v_bfe_u32 v22, v12, 16, 1
	v_add3_u32 v12, v12, v22, s27
	global_store_short_d16_hi v[34:35], v12, off offset:64
	v_bfe_u32 v12, v8, 16, 1
	v_add3_u32 v8, v8, v12, s27
	global_store_short_d16_hi v[36:37], v8, off offset:64
	v_bfe_u32 v8, v13, 16, 1
	v_add3_u32 v8, v13, v8, s27
	global_store_short_d16_hi v[38:39], v8, off offset:64
	v_bfe_u32 v8, v9, 16, 1
	v_add3_u32 v8, v9, v8, s27
	global_store_short_d16_hi v[16:17], v8, off offset:64
	v_bfe_u32 v8, v14, 16, 1
	v_add3_u32 v8, v14, v8, s27
	global_store_short_d16_hi v[40:41], v8, off offset:64
	v_bfe_u32 v8, v10, 16, 1
	v_add3_u32 v8, v10, v8, s27
	global_store_short_d16_hi v[20:21], v8, off offset:64
	v_bfe_u32 v8, v15, 16, 1
	v_add3_u32 v8, v15, v8, s27
	global_store_short_d16_hi v[32:33], v8, off offset:64
	v_bfe_u32 v8, v11, 16, 1
	v_add3_u32 v8, v11, v8, s27
	global_store_short_d16_hi v[18:19], v8, off offset:64
	v_bfe_u32 v8, v4, 16, 1
	v_add3_u32 v4, v4, v8, s27
	global_store_short_d16_hi v[34:35], v4, off offset:96
	v_bfe_u32 v4, v0, 16, 1
	v_add3_u32 v0, v0, v4, s27
	global_store_short_d16_hi v[36:37], v0, off offset:96
	v_bfe_u32 v0, v5, 16, 1
	v_add3_u32 v0, v5, v0, s27
	global_store_short_d16_hi v[38:39], v0, off offset:96
	v_bfe_u32 v0, v1, 16, 1
	v_add3_u32 v0, v1, v0, s27
	global_store_short_d16_hi v[16:17], v0, off offset:96
	v_bfe_u32 v0, v6, 16, 1
	v_add3_u32 v0, v6, v0, s27
	global_store_short_d16_hi v[40:41], v0, off offset:96
	v_bfe_u32 v0, v2, 16, 1
	v_add3_u32 v0, v2, v0, s27
	global_store_short_d16_hi v[20:21], v0, off offset:96
	v_bfe_u32 v0, v7, 16, 1
	v_add3_u32 v0, v7, v0, s27
	global_store_short_d16_hi v[32:33], v0, off offset:96
	v_bfe_u32 v0, v3, 16, 1
	s_addk_i32 s55, 0x80
	v_add3_u32 v0, v3, v0, s27
	s_cmpk_eq_i32 s55, 0x180
	global_store_short_d16_hi v[18:19], v0, off offset:96
	s_waitcnt vmcnt(63) expcnt(7) lgkmcnt(15)
	s_barrier
	s_cbranch_scc0 .LBB0_618
	s_waitcnt vmcnt(0)
	s_add_u32 s12, s10, 0x3700
	s_addc_u32 s13, s11, 0
	s_barrier
	v_mbcnt_lo_u32_b32 v0, -1, 0
	v_mbcnt_hi_u32_b32 v0, -1, v0
	s_nop 0
	v_cmp_eq_u32_e32 vcc, s74, v0
	s_and_saveexec_b64 s[8:9], vcc
	s_cbranch_execz .LBB0_636
	s_mov_b64 s[18:19], exec
	buffer_wbl2 sc1
	buffer_inv sc1
	s_waitcnt vmcnt(0)
	s_waitcnt vmcnt(0)
	v_mbcnt_lo_u32_b32 v0, s18, 0
	v_mbcnt_hi_u32_b32 v0, s19, v0
	v_cmp_eq_u32_e32 vcc, 0, v0
	s_and_saveexec_b64 s[20:21], vcc
	s_cbranch_execz .LBB0_622
	s_bcnt1_i32_b64 s18, s[18:19]
	v_mov_b32_e32 v0, 0
	v_mov_b32_e32 v1, s18
	global_atomic_add v0, v1, s[12:13]
